# gemm_stream K-loops: loop-head DMA-address SALU sunk below the first 8 LDS fragment reads (loop-edge edit)
# speedup vs baseline: 1.0016x; 1.0016x over previous
.LBB0_33:
	s_add_i32 s63, 0, 0x10000
	s_add_i32 s64, 0, 0x14000
	v_add_u32_e32 v64, s63, v78
	ds_read_b128 v[138:141], v64
	ds_read_b128 v[142:145], v64 offset:1024
	ds_read_b128 v[146:149], v64 offset:2048
	ds_read_b128 v[150:153], v64 offset:3072
	v_add_u32_e32 v64, s64, v78
	ds_read_b128 v[154:157], v64
	ds_read_b128 v[158:161], v64 offset:1024
	ds_read_b128 v[162:165], v64 offset:2048
	ds_read_b128 v[166:169], v64 offset:3072
	s_add_u32 s60, s56, s92
	s_addc_u32 s61, s57, s93
	s_add_u32 s2, s60, 0x2500100
	s_addc_u32 s3, s61, 0
	s_add_u32 s54, s58, s92
	s_addc_u32 s55, s59, s93
	s_cmpk_eq_i32 s92, 0x1f00
	s_cselect_b32 s3, s47, s3
	s_cselect_b32 s2, s46, s2
	s_cselect_b32 s55, s41, s55
	s_cselect_b32 s54, s40, s54
	v_mov_b32_e32 v64, v74
	ds_read_b128 v[170:173], v79
	ds_read_b128 v[174:177], v79 offset:1024
	ds_read_b128 v[178:181], v79 offset:2048
	ds_read_b128 v[182:185], v79 offset:3072
	ds_read_b128 v[190:193], v79 offset:4096
	ds_read_b128 v[194:197], v79 offset:5120
	ds_read_b128 v[198:201], v79 offset:6144
	ds_read_b128 v[214:217], v79 offset:7168
	s_add_i32 m0, s17, 0xc000
	v_lshl_add_u64 v[80:81], s[60:61], 0, v[64:65]
	v_lshl_add_u64 v[80:81], v[80:81], 0, s[66:67]
	v_mov_b32_e32 v64, v76
	global_load_lds_dwordx4 v[80:81], off
	s_add_i32 m0, s17, 0xe000
	v_lshl_add_u64 v[80:81], s[60:61], 0, v[64:65]
	v_lshl_add_u64 v[80:81], v[80:81], 0, s[66:67]
	global_load_lds_dwordx4 v[80:81], off
	s_waitcnt vmcnt(8)
	s_waitcnt lgkmcnt(0)
	s_barrier
	s_setprio 1
	s_waitcnt lgkmcnt(0)
	v_mfma_f32_16x16x32_bf16 v[70:73], v[138:141], v[170:173], v[70:73]
	v_mfma_f32_16x16x32_bf16 v[56:59], v[146:149], v[170:173], v[56:59]
	v_mfma_f32_16x16x32_bf16 v[126:129], v[138:141], v[178:181], v[126:129]
	v_mfma_f32_16x16x32_bf16 v[122:125], v[146:149], v[178:181], v[122:125]
	v_mfma_f32_16x16x32_bf16 v[110:113], v[138:141], v[190:193], v[110:113]
	v_mfma_f32_16x16x32_bf16 v[106:109], v[146:149], v[190:193], v[106:109]
	v_mfma_f32_16x16x32_bf16 v[94:97], v[138:141], v[198:201], v[94:97]
	v_mfma_f32_16x16x32_bf16 v[90:93], v[146:149], v[198:201], v[90:93]
	v_mfma_f32_16x16x32_bf16 v[70:73], v[142:145], v[174:177], v[70:73]
	v_mfma_f32_16x16x32_bf16 v[56:59], v[150:153], v[174:177], v[56:59]
	v_mfma_f32_16x16x32_bf16 v[126:129], v[142:145], v[182:185], v[126:129]
	v_mfma_f32_16x16x32_bf16 v[122:125], v[150:153], v[182:185], v[122:125]
	v_mfma_f32_16x16x32_bf16 v[110:113], v[142:145], v[194:197], v[110:113]
	v_mfma_f32_16x16x32_bf16 v[106:109], v[150:153], v[194:197], v[106:109]
	v_mfma_f32_16x16x32_bf16 v[94:97], v[142:145], v[214:217], v[94:97]
	v_mfma_f32_16x16x32_bf16 v[90:93], v[150:153], v[214:217], v[90:93]
	s_setprio 0
	s_setprio 1
	v_mfma_f32_16x16x32_bf16 v[134:137], v[154:157], v[170:173], v[134:137]
	v_mfma_f32_16x16x32_bf16 v[130:133], v[162:165], v[170:173], v[130:133]
	v_mfma_f32_16x16x32_bf16 v[118:121], v[154:157], v[178:181], v[118:121]
	v_mfma_f32_16x16x32_bf16 v[114:117], v[162:165], v[178:181], v[114:117]
	v_mfma_f32_16x16x32_bf16 v[102:105], v[154:157], v[190:193], v[102:105]
	v_mfma_f32_16x16x32_bf16 v[98:101], v[162:165], v[190:193], v[98:101]
	v_mfma_f32_16x16x32_bf16 v[86:89], v[154:157], v[198:201], v[86:89]
	v_mfma_f32_16x16x32_bf16 v[80:83], v[162:165], v[198:201], v[82:85]
	v_mfma_f32_16x16x32_bf16 v[134:137], v[158:161], v[174:177], v[134:137]
	v_mfma_f32_16x16x32_bf16 v[130:133], v[166:169], v[174:177], v[130:133]
	v_mfma_f32_16x16x32_bf16 v[118:121], v[158:161], v[182:185], v[118:121]
	v_mfma_f32_16x16x32_bf16 v[114:117], v[166:169], v[182:185], v[114:117]
	v_mfma_f32_16x16x32_bf16 v[102:105], v[158:161], v[194:197], v[102:105]
	v_mfma_f32_16x16x32_bf16 v[98:101], v[166:169], v[194:197], v[98:101]
	v_mfma_f32_16x16x32_bf16 v[86:89], v[158:161], v[214:217], v[86:89]
	v_mfma_f32_16x16x32_bf16 v[80:83], v[166:169], v[214:217], v[80:83]
	s_setprio 0
	s_barrier
	v_mov_b32_e32 v64, v75
	s_add_i32 s60, s63, s11
	ds_read_b128 v[170:173], v79 offset:16384
	ds_read_b128 v[174:177], v79 offset:17408
	ds_read_b128 v[178:181], v79 offset:18432
	ds_read_b128 v[182:185], v79 offset:19456
	ds_read_b128 v[190:193], v79 offset:20480
	ds_read_b128 v[194:197], v79 offset:21504
	ds_read_b128 v[198:201], v79 offset:22528
	ds_read_b128 v[214:217], v79 offset:23552
	s_mov_b32 m0, s60
	s_nop 0
	global_load_lds_dwordx4 v64, s[54:55]
	v_mov_b32_e32 v64, v77
	s_add_i32 m0, s60, 0x2000
	s_add_u32 s60, s54, 0x100000
	global_load_lds_dwordx4 v64, s[54:55]
	s_addc_u32 s61, s55, 0
	v_mov_b32_e32 v64, v75
	s_add_i32 s63, s64, s11
	s_mov_b32 m0, s63
	s_nop 0
	global_load_lds_dwordx4 v64, s[60:61]
	v_mov_b32_e32 v64, v77
	s_add_i32 m0, s63, 0x2000
	s_nop 0
	global_load_lds_dwordx4 v64, s[60:61]
	v_mov_b32_e32 v64, v74
	s_mov_b32 m0, s17
	s_nop 0
	global_load_lds_dwordx4 v64, s[2:3]
	v_mov_b32_e32 v64, v76
	s_mov_b32 m0, s22
	s_nop 0
	global_load_lds_dwordx4 v64, s[2:3]
	s_waitcnt vmcnt(8)
	s_waitcnt lgkmcnt(0)
	s_barrier
	s_setprio 1
	s_waitcnt lgkmcnt(0)
	v_mfma_f32_16x16x32_bf16 v[66:69], v[138:141], v[170:173], v[66:69]
	v_mfma_f32_16x16x32_bf16 v[60:63], v[146:149], v[170:173], v[60:63]
	v_mfma_f32_16x16x32_bf16 v[44:47], v[138:141], v[178:181], v[44:47]
	v_mfma_f32_16x16x32_bf16 v[40:43], v[146:149], v[178:181], v[40:43]
	v_mfma_f32_16x16x32_bf16 v[28:31], v[138:141], v[190:193], v[28:31]
	v_mfma_f32_16x16x32_bf16 v[24:27], v[146:149], v[190:193], v[24:27]
	v_mfma_f32_16x16x32_bf16 v[12:15], v[138:141], v[198:201], v[12:15]
	v_mfma_f32_16x16x32_bf16 v[8:11], v[146:149], v[198:201], v[8:11]
	v_mfma_f32_16x16x32_bf16 v[66:69], v[142:145], v[174:177], v[66:69]
	v_mfma_f32_16x16x32_bf16 v[60:63], v[150:153], v[174:177], v[60:63]
	v_mfma_f32_16x16x32_bf16 v[44:47], v[142:145], v[182:185], v[44:47]
	v_mfma_f32_16x16x32_bf16 v[40:43], v[150:153], v[182:185], v[40:43]
	v_mfma_f32_16x16x32_bf16 v[28:31], v[142:145], v[194:197], v[28:31]
	v_mfma_f32_16x16x32_bf16 v[24:27], v[150:153], v[194:197], v[24:27]
	v_mfma_f32_16x16x32_bf16 v[12:15], v[142:145], v[214:217], v[12:15]
	v_mfma_f32_16x16x32_bf16 v[8:11], v[150:153], v[214:217], v[8:11]
	s_setprio 0
	s_setprio 1
	v_mfma_f32_16x16x32_bf16 v[52:55], v[154:157], v[170:173], v[52:55]
	v_mfma_f32_16x16x32_bf16 v[48:51], v[162:165], v[170:173], v[48:51]
	v_mfma_f32_16x16x32_bf16 v[36:39], v[154:157], v[178:181], v[36:39]
	v_mfma_f32_16x16x32_bf16 v[32:35], v[162:165], v[178:181], v[32:35]
	v_mfma_f32_16x16x32_bf16 v[20:23], v[154:157], v[190:193], v[20:23]
	v_mfma_f32_16x16x32_bf16 v[16:19], v[162:165], v[190:193], v[16:19]
	v_mfma_f32_16x16x32_bf16 v[4:7], v[154:157], v[198:201], v[4:7]
	v_mfma_f32_16x16x32_bf16 v[0:3], v[162:165], v[198:201], v[0:3]
	v_mfma_f32_16x16x32_bf16 v[52:55], v[158:161], v[174:177], v[52:55]
	v_mfma_f32_16x16x32_bf16 v[48:51], v[166:169], v[174:177], v[48:51]
	v_mfma_f32_16x16x32_bf16 v[36:39], v[158:161], v[182:185], v[36:39]
	v_mfma_f32_16x16x32_bf16 v[32:35], v[166:169], v[182:185], v[32:35]
	v_mfma_f32_16x16x32_bf16 v[20:23], v[158:161], v[194:197], v[20:23]
	v_mfma_f32_16x16x32_bf16 v[16:19], v[166:169], v[194:197], v[16:19]
	v_mfma_f32_16x16x32_bf16 v[4:7], v[158:161], v[214:217], v[4:7]
	v_mfma_f32_16x16x32_bf16 v[0:3], v[166:169], v[214:217], v[0:3]
	s_setprio 0
	s_barrier
	s_add_i32 s63, 0, 0x18000
	v_add_u32_e32 v64, s63, v78
	s_add_i32 s64, 0, 0x1c000
	ds_read_b128 v[138:141], v64
	ds_read_b128 v[142:145], v64 offset:1024
	ds_read_b128 v[146:149], v64 offset:2048
	ds_read_b128 v[150:153], v64 offset:3072
	v_add_u32_e32 v64, s64, v78
	ds_read_b128 v[154:157], v64
	ds_read_b128 v[158:161], v64 offset:1024
	ds_read_b128 v[162:165], v64 offset:2048
	ds_read_b128 v[166:169], v64 offset:3072
	s_add_u32 s60, s2, 0x100000
	v_mov_b32_e32 v64, v74
	s_mov_b32 m0, s49
	ds_read_b128 v[170:173], v79 offset:32768
	ds_read_b128 v[174:177], v79 offset:33792
	ds_read_b128 v[178:181], v79 offset:34816
	ds_read_b128 v[182:185], v79 offset:35840
	ds_read_b128 v[190:193], v79 offset:36864
	ds_read_b128 v[194:197], v79 offset:37888
	ds_read_b128 v[198:201], v79 offset:38912
	ds_read_b128 v[214:217], v79 offset:39936
	s_addc_u32 s61, s3, 0
	s_nop 0
	global_load_lds_dwordx4 v64, s[60:61]
	v_mov_b32_e32 v64, v76
	s_mov_b32 m0, s50
	s_nop 0
	global_load_lds_dwordx4 v64, s[60:61]
	s_waitcnt vmcnt(8)
	s_waitcnt lgkmcnt(0)
	s_barrier
	s_setprio 1
	s_waitcnt lgkmcnt(0)
	v_mfma_f32_16x16x32_bf16 v[70:73], v[138:141], v[170:173], v[70:73]
	v_mfma_f32_16x16x32_bf16 v[56:59], v[146:149], v[170:173], v[56:59]
	v_mfma_f32_16x16x32_bf16 v[126:129], v[138:141], v[178:181], v[126:129]
	v_mfma_f32_16x16x32_bf16 v[122:125], v[146:149], v[178:181], v[122:125]
	v_mfma_f32_16x16x32_bf16 v[110:113], v[138:141], v[190:193], v[110:113]
	v_mfma_f32_16x16x32_bf16 v[106:109], v[146:149], v[190:193], v[106:109]
	v_mfma_f32_16x16x32_bf16 v[94:97], v[138:141], v[198:201], v[94:97]
	v_mfma_f32_16x16x32_bf16 v[90:93], v[146:149], v[198:201], v[90:93]
	v_mfma_f32_16x16x32_bf16 v[70:73], v[142:145], v[174:177], v[70:73]
	v_mfma_f32_16x16x32_bf16 v[56:59], v[150:153], v[174:177], v[56:59]
	v_mfma_f32_16x16x32_bf16 v[126:129], v[142:145], v[182:185], v[126:129]
	v_mfma_f32_16x16x32_bf16 v[122:125], v[150:153], v[182:185], v[122:125]
	v_mfma_f32_16x16x32_bf16 v[110:113], v[142:145], v[194:197], v[110:113]
	v_mfma_f32_16x16x32_bf16 v[106:109], v[150:153], v[194:197], v[106:109]
	v_mfma_f32_16x16x32_bf16 v[94:97], v[142:145], v[214:217], v[94:97]
	v_mfma_f32_16x16x32_bf16 v[90:93], v[150:153], v[214:217], v[90:93]
	s_setprio 0
	s_setprio 1
	v_mfma_f32_16x16x32_bf16 v[134:137], v[154:157], v[170:173], v[134:137]
	v_mfma_f32_16x16x32_bf16 v[130:133], v[162:165], v[170:173], v[130:133]
	v_mfma_f32_16x16x32_bf16 v[118:121], v[154:157], v[178:181], v[118:121]
	v_mfma_f32_16x16x32_bf16 v[114:117], v[162:165], v[178:181], v[114:117]
	v_mfma_f32_16x16x32_bf16 v[102:105], v[154:157], v[190:193], v[102:105]
	v_mfma_f32_16x16x32_bf16 v[98:101], v[162:165], v[190:193], v[98:101]
	v_mfma_f32_16x16x32_bf16 v[84:87], v[154:157], v[198:201], v[86:89]
	v_mfma_f32_16x16x32_bf16 v[80:83], v[162:165], v[198:201], v[80:83]
	v_mfma_f32_16x16x32_bf16 v[134:137], v[158:161], v[174:177], v[134:137]
	v_mfma_f32_16x16x32_bf16 v[130:133], v[166:169], v[174:177], v[130:133]
	v_mfma_f32_16x16x32_bf16 v[118:121], v[158:161], v[182:185], v[118:121]
	v_mfma_f32_16x16x32_bf16 v[114:117], v[166:169], v[182:185], v[114:117]
	v_mfma_f32_16x16x32_bf16 v[102:105], v[158:161], v[194:197], v[102:105]
	v_mfma_f32_16x16x32_bf16 v[98:101], v[166:169], v[194:197], v[98:101]
	v_mfma_f32_16x16x32_bf16 v[86:89], v[158:161], v[214:217], v[84:87]
	v_mfma_f32_16x16x32_bf16 v[82:85], v[166:169], v[214:217], v[80:83]
	s_setprio 0
	s_barrier
	v_mov_b32_e32 v64, v75
	ds_read_b128 v[170:173], v79 offset:49152
	ds_read_b128 v[174:177], v79 offset:50176
	ds_read_b128 v[178:181], v79 offset:51200
	ds_read_b128 v[182:185], v79 offset:52224
	ds_read_b128 v[190:193], v79 offset:53248
	ds_read_b128 v[194:197], v79 offset:54272
	ds_read_b128 v[198:201], v79 offset:55296
	ds_read_b128 v[214:217], v79 offset:56320
	s_add_i32 s60, s63, s11
	v_lshl_add_u64 v[80:81], s[54:55], 0, v[64:65]
	v_lshl_add_u64 v[80:81], v[80:81], 0, s[24:25]
	s_mov_b32 m0, s60
	v_mov_b32_e32 v64, v77
	global_load_lds_dwordx4 v[80:81], off
	s_add_i32 m0, s60, 0x2000
	s_nop 0
	v_lshl_add_u64 v[80:81], s[54:55], 0, v[64:65]
	s_add_u32 s54, s54, 0x100080
	v_lshl_add_u64 v[80:81], v[80:81], 0, s[24:25]
	s_addc_u32 s55, s55, 0
	v_mov_b32_e32 v64, v75
	s_add_i32 s60, s64, s11
	global_load_lds_dwordx4 v[80:81], off
	s_mov_b32 m0, s60
	s_nop 0
	global_load_lds_dwordx4 v64, s[54:55]
	v_mov_b32_e32 v64, v77
	s_add_i32 m0, s60, 0x2000
	s_nop 0
	global_load_lds_dwordx4 v64, s[54:55]
	v_mov_b32_e32 v64, v74
	s_mov_b32 m0, s52
	v_lshl_add_u64 v[80:81], s[2:3], 0, v[64:65]
	v_lshl_add_u64 v[80:81], v[80:81], 0, s[24:25]
	v_mov_b32_e32 v64, v76
	global_load_lds_dwordx4 v[80:81], off
	s_mov_b32 m0, s53
	v_lshl_add_u64 v[80:81], s[2:3], 0, v[64:65]
	v_lshl_add_u64 v[80:81], v[80:81], 0, s[24:25]
	global_load_lds_dwordx4 v[80:81], off
	s_waitcnt vmcnt(8)
	s_waitcnt lgkmcnt(0)
	s_barrier
	s_setprio 1
	s_waitcnt lgkmcnt(0)
	v_mfma_f32_16x16x32_bf16 v[66:69], v[138:141], v[170:173], v[66:69]
	v_mfma_f32_16x16x32_bf16 v[60:63], v[146:149], v[170:173], v[60:63]
	v_mfma_f32_16x16x32_bf16 v[44:47], v[138:141], v[178:181], v[44:47]
	v_mfma_f32_16x16x32_bf16 v[40:43], v[146:149], v[178:181], v[40:43]
	v_mfma_f32_16x16x32_bf16 v[28:31], v[138:141], v[190:193], v[28:31]
	v_mfma_f32_16x16x32_bf16 v[24:27], v[146:149], v[190:193], v[24:27]
	v_mfma_f32_16x16x32_bf16 v[12:15], v[138:141], v[198:201], v[12:15]
	v_mfma_f32_16x16x32_bf16 v[8:11], v[146:149], v[198:201], v[8:11]
	v_mfma_f32_16x16x32_bf16 v[66:69], v[142:145], v[174:177], v[66:69]
	v_mfma_f32_16x16x32_bf16 v[60:63], v[150:153], v[174:177], v[60:63]
	v_mfma_f32_16x16x32_bf16 v[44:47], v[142:145], v[182:185], v[44:47]
	v_mfma_f32_16x16x32_bf16 v[40:43], v[150:153], v[182:185], v[40:43]
	v_mfma_f32_16x16x32_bf16 v[28:31], v[142:145], v[194:197], v[28:31]
	v_mfma_f32_16x16x32_bf16 v[24:27], v[150:153], v[194:197], v[24:27]
	v_mfma_f32_16x16x32_bf16 v[12:15], v[142:145], v[214:217], v[12:15]
	v_mfma_f32_16x16x32_bf16 v[8:11], v[150:153], v[214:217], v[8:11]
	s_setprio 0
	s_setprio 1
	v_mfma_f32_16x16x32_bf16 v[52:55], v[154:157], v[170:173], v[52:55]
	v_mfma_f32_16x16x32_bf16 v[48:51], v[162:165], v[170:173], v[48:51]
	v_mfma_f32_16x16x32_bf16 v[36:39], v[154:157], v[178:181], v[36:39]
	v_mfma_f32_16x16x32_bf16 v[32:35], v[162:165], v[178:181], v[32:35]
	v_mfma_f32_16x16x32_bf16 v[20:23], v[154:157], v[190:193], v[20:23]
	v_mfma_f32_16x16x32_bf16 v[16:19], v[162:165], v[190:193], v[16:19]
	v_mfma_f32_16x16x32_bf16 v[4:7], v[154:157], v[198:201], v[4:7]
	v_mfma_f32_16x16x32_bf16 v[0:3], v[162:165], v[198:201], v[0:3]
	v_mfma_f32_16x16x32_bf16 v[52:55], v[158:161], v[174:177], v[52:55]
	v_mfma_f32_16x16x32_bf16 v[48:51], v[166:169], v[174:177], v[48:51]
	v_mfma_f32_16x16x32_bf16 v[36:39], v[158:161], v[182:185], v[36:39]
	v_mfma_f32_16x16x32_bf16 v[32:35], v[166:169], v[182:185], v[32:35]
	v_mfma_f32_16x16x32_bf16 v[20:23], v[158:161], v[194:197], v[20:23]
	v_mfma_f32_16x16x32_bf16 v[16:19], v[166:169], v[194:197], v[16:19]
	v_mfma_f32_16x16x32_bf16 v[4:7], v[158:161], v[214:217], v[4:7]
	v_mfma_f32_16x16x32_bf16 v[0:3], v[166:169], v[214:217], v[0:3]
	s_setprio 0
	s_barrier
	s_add_i32 s62, s62, 2
	s_add_u32 s92, s92, 0x100
	s_addc_u32 s93, s93, 0
	s_cmp_gt_u32 s62, 61
	s_cbranch_scc0 .LBB0_33
	s_cmp_lt_u32 s48, 4
	s_cbranch_scc0 .LBB0_36
	s_barrier

.LBB0_80:
	s_add_i32 s60, 0, 0x10000
	s_add_i32 s70, 0, 0x14000
	v_add_u32_e32 v64, s60, v136
	ds_read_b128 v[138:141], v64
	ds_read_b128 v[142:145], v64 offset:1024
	ds_read_b128 v[146:149], v64 offset:2048
	ds_read_b128 v[150:153], v64 offset:3072
	v_add_u32_e32 v64, s70, v136
	ds_read_b128 v[154:157], v64
	ds_read_b128 v[158:161], v64 offset:1024
	ds_read_b128 v[162:165], v64 offset:2048
	ds_read_b128 v[166:169], v64 offset:3072
	s_add_u32 s2, s94, 0xfffc0080
	s_addc_u32 s3, s95, -1
	s_cmp_eq_u32 s69, 12
	s_cselect_b32 s3, s63, s3
	s_cselect_b32 s2, s64, s2
	s_cselect_b32 s55, s65, s68
	s_cselect_b32 s54, s66, s67
	v_mov_b32_e32 v64, v132
	ds_read_b128 v[170:173], v137
	ds_read_b128 v[174:177], v137 offset:1024
	ds_read_b128 v[178:181], v137 offset:2048
	ds_read_b128 v[182:185], v137 offset:3072
	ds_read_b128 v[190:193], v137 offset:4096
	ds_read_b128 v[194:197], v137 offset:5120
	ds_read_b128 v[198:201], v137 offset:6144
	ds_read_b128 v[214:217], v137 offset:7168
	s_add_i32 m0, s50, 0xc000
	s_nop 0
	global_load_lds_dwordx4 v64, s[94:95]
	v_mov_b32_e32 v64, v134
	s_add_i32 m0, s50, 0xe000
	s_nop 0
	global_load_lds_dwordx4 v64, s[94:95]
	s_waitcnt vmcnt(8)
	s_waitcnt lgkmcnt(0)
	s_barrier
	s_setprio 1
	s_waitcnt lgkmcnt(0)
	v_mfma_f32_16x16x32_bf16 v[126:129], v[138:141], v[170:173], v[126:129]
	v_mfma_f32_16x16x32_bf16 v[122:125], v[146:149], v[170:173], v[122:125]
	v_mfma_f32_16x16x32_bf16 v[110:113], v[138:141], v[178:181], v[110:113]
	v_mfma_f32_16x16x32_bf16 v[106:109], v[146:149], v[178:181], v[106:109]
	v_mfma_f32_16x16x32_bf16 v[94:97], v[138:141], v[190:193], v[94:97]
	v_mfma_f32_16x16x32_bf16 v[90:93], v[146:149], v[190:193], v[90:93]
	v_mfma_f32_16x16x32_bf16 v[78:81], v[138:141], v[198:201], v[78:81]
	v_mfma_f32_16x16x32_bf16 v[74:77], v[146:149], v[198:201], v[74:77]
	v_mfma_f32_16x16x32_bf16 v[126:129], v[142:145], v[174:177], v[126:129]
	v_mfma_f32_16x16x32_bf16 v[122:125], v[150:153], v[174:177], v[122:125]
	v_mfma_f32_16x16x32_bf16 v[110:113], v[142:145], v[182:185], v[110:113]
	v_mfma_f32_16x16x32_bf16 v[106:109], v[150:153], v[182:185], v[106:109]
	v_mfma_f32_16x16x32_bf16 v[94:97], v[142:145], v[194:197], v[94:97]
	v_mfma_f32_16x16x32_bf16 v[90:93], v[150:153], v[194:197], v[90:93]
	v_mfma_f32_16x16x32_bf16 v[78:81], v[142:145], v[214:217], v[78:81]
	v_mfma_f32_16x16x32_bf16 v[74:77], v[150:153], v[214:217], v[74:77]
	s_setprio 0
	s_setprio 1
	v_mfma_f32_16x16x32_bf16 v[118:121], v[154:157], v[170:173], v[118:121]
	v_mfma_f32_16x16x32_bf16 v[114:117], v[162:165], v[170:173], v[114:117]
	v_mfma_f32_16x16x32_bf16 v[102:105], v[154:157], v[178:181], v[102:105]
	v_mfma_f32_16x16x32_bf16 v[98:101], v[162:165], v[178:181], v[98:101]
	v_mfma_f32_16x16x32_bf16 v[86:89], v[154:157], v[190:193], v[86:89]
	v_mfma_f32_16x16x32_bf16 v[82:85], v[162:165], v[190:193], v[82:85]
	v_mfma_f32_16x16x32_bf16 v[70:73], v[154:157], v[198:201], v[70:73]
	v_mfma_f32_16x16x32_bf16 v[66:69], v[162:165], v[198:201], v[66:69]
	v_mfma_f32_16x16x32_bf16 v[118:121], v[158:161], v[174:177], v[118:121]
	v_mfma_f32_16x16x32_bf16 v[114:117], v[166:169], v[174:177], v[114:117]
	v_mfma_f32_16x16x32_bf16 v[102:105], v[158:161], v[182:185], v[102:105]
	v_mfma_f32_16x16x32_bf16 v[98:101], v[166:169], v[182:185], v[98:101]
	v_mfma_f32_16x16x32_bf16 v[86:89], v[158:161], v[194:197], v[86:89]
	v_mfma_f32_16x16x32_bf16 v[82:85], v[166:169], v[194:197], v[82:85]
	v_mfma_f32_16x16x32_bf16 v[70:73], v[158:161], v[214:217], v[70:73]
	v_mfma_f32_16x16x32_bf16 v[66:69], v[166:169], v[214:217], v[66:69]
	s_setprio 0
	s_barrier
	v_mov_b32_e32 v64, v133
	s_add_i32 s60, s60, s49
	ds_read_b128 v[170:173], v137 offset:16384
	ds_read_b128 v[174:177], v137 offset:17408
	ds_read_b128 v[178:181], v137 offset:18432
	ds_read_b128 v[182:185], v137 offset:19456
	ds_read_b128 v[190:193], v137 offset:20480
	ds_read_b128 v[194:197], v137 offset:21504
	ds_read_b128 v[198:201], v137 offset:22528
	ds_read_b128 v[214:217], v137 offset:23552
	s_mov_b32 m0, s60
	s_nop 0
	global_load_lds_dwordx4 v64, s[54:55]
	v_mov_b32_e32 v64, v135
	s_add_i32 m0, s60, 0x2000
	s_add_u32 s60, s54, 0x40000
	global_load_lds_dwordx4 v64, s[54:55]
	s_addc_u32 s61, s55, 0
	v_mov_b32_e32 v64, v133
	s_add_i32 s70, s70, s49
	s_mov_b32 m0, s70
	s_nop 0
	global_load_lds_dwordx4 v64, s[60:61]
	v_mov_b32_e32 v64, v135
	s_add_i32 m0, s70, 0x2000
	s_nop 0
	global_load_lds_dwordx4 v64, s[60:61]
	v_mov_b32_e32 v64, v132
	s_mov_b32 m0, s50
	s_nop 0
	global_load_lds_dwordx4 v64, s[2:3]
	v_mov_b32_e32 v64, v134
	s_mov_b32 m0, s51
	s_nop 0
	global_load_lds_dwordx4 v64, s[2:3]
	s_waitcnt vmcnt(8)
	s_waitcnt lgkmcnt(0)
	s_barrier
	s_setprio 1
	s_waitcnt lgkmcnt(0)
	v_mfma_f32_16x16x32_bf16 v[60:63], v[138:141], v[170:173], v[60:63]
	v_mfma_f32_16x16x32_bf16 v[56:59], v[146:149], v[170:173], v[56:59]
	v_mfma_f32_16x16x32_bf16 v[44:47], v[138:141], v[178:181], v[44:47]
	v_mfma_f32_16x16x32_bf16 v[40:43], v[146:149], v[178:181], v[40:43]
	v_mfma_f32_16x16x32_bf16 v[28:31], v[138:141], v[190:193], v[28:31]
	v_mfma_f32_16x16x32_bf16 v[24:27], v[146:149], v[190:193], v[24:27]
	v_mfma_f32_16x16x32_bf16 v[12:15], v[138:141], v[198:201], v[12:15]
	v_mfma_f32_16x16x32_bf16 v[8:11], v[146:149], v[198:201], v[8:11]
	v_mfma_f32_16x16x32_bf16 v[60:63], v[142:145], v[174:177], v[60:63]
	v_mfma_f32_16x16x32_bf16 v[56:59], v[150:153], v[174:177], v[56:59]
	v_mfma_f32_16x16x32_bf16 v[44:47], v[142:145], v[182:185], v[44:47]
	v_mfma_f32_16x16x32_bf16 v[40:43], v[150:153], v[182:185], v[40:43]
	v_mfma_f32_16x16x32_bf16 v[28:31], v[142:145], v[194:197], v[28:31]
	v_mfma_f32_16x16x32_bf16 v[24:27], v[150:153], v[194:197], v[24:27]
	v_mfma_f32_16x16x32_bf16 v[12:15], v[142:145], v[214:217], v[12:15]
	v_mfma_f32_16x16x32_bf16 v[8:11], v[150:153], v[214:217], v[8:11]
	s_setprio 0
	s_setprio 1
	v_mfma_f32_16x16x32_bf16 v[52:55], v[154:157], v[170:173], v[52:55]
	v_mfma_f32_16x16x32_bf16 v[48:51], v[162:165], v[170:173], v[48:51]
	v_mfma_f32_16x16x32_bf16 v[36:39], v[154:157], v[178:181], v[36:39]
	v_mfma_f32_16x16x32_bf16 v[32:35], v[162:165], v[178:181], v[32:35]
	v_mfma_f32_16x16x32_bf16 v[20:23], v[154:157], v[190:193], v[20:23]
	v_mfma_f32_16x16x32_bf16 v[16:19], v[162:165], v[190:193], v[16:19]
	v_mfma_f32_16x16x32_bf16 v[4:7], v[154:157], v[198:201], v[4:7]
	v_mfma_f32_16x16x32_bf16 v[0:3], v[162:165], v[198:201], v[0:3]
	v_mfma_f32_16x16x32_bf16 v[52:55], v[158:161], v[174:177], v[52:55]
	v_mfma_f32_16x16x32_bf16 v[48:51], v[166:169], v[174:177], v[48:51]
	v_mfma_f32_16x16x32_bf16 v[36:39], v[158:161], v[182:185], v[36:39]
	v_mfma_f32_16x16x32_bf16 v[32:35], v[166:169], v[182:185], v[32:35]
	v_mfma_f32_16x16x32_bf16 v[20:23], v[158:161], v[194:197], v[20:23]
	v_mfma_f32_16x16x32_bf16 v[16:19], v[166:169], v[194:197], v[16:19]
	v_mfma_f32_16x16x32_bf16 v[4:7], v[158:161], v[214:217], v[4:7]
	v_mfma_f32_16x16x32_bf16 v[0:3], v[166:169], v[214:217], v[0:3]
	s_setprio 0
	s_barrier
	s_add_i32 s70, 0, 0x18000
	v_add_u32_e32 v64, s70, v136
	s_add_i32 s71, 0, 0x1c000
	ds_read_b128 v[138:141], v64
	ds_read_b128 v[142:145], v64 offset:1024
	ds_read_b128 v[146:149], v64 offset:2048
	ds_read_b128 v[150:153], v64 offset:3072
	v_add_u32_e32 v64, s71, v136
	ds_read_b128 v[154:157], v64
	ds_read_b128 v[158:161], v64 offset:1024
	ds_read_b128 v[162:165], v64 offset:2048
	ds_read_b128 v[166:169], v64 offset:3072
	s_add_u32 s60, s2, 0x40000
	v_mov_b32_e32 v64, v132
	s_mov_b32 m0, s52
	ds_read_b128 v[170:173], v137 offset:32768
	ds_read_b128 v[174:177], v137 offset:33792
	ds_read_b128 v[178:181], v137 offset:34816
	ds_read_b128 v[182:185], v137 offset:35840
	ds_read_b128 v[190:193], v137 offset:36864
	ds_read_b128 v[194:197], v137 offset:37888
	ds_read_b128 v[198:201], v137 offset:38912
	ds_read_b128 v[214:217], v137 offset:39936
	s_addc_u32 s61, s3, 0
	s_nop 0
	global_load_lds_dwordx4 v64, s[60:61]
	v_mov_b32_e32 v64, v134
	s_mov_b32 m0, s53
	s_nop 0
	global_load_lds_dwordx4 v64, s[60:61]
	s_waitcnt vmcnt(8)
	s_waitcnt lgkmcnt(0)
	s_barrier
	s_setprio 1
	s_waitcnt lgkmcnt(0)
	v_mfma_f32_16x16x32_bf16 v[126:129], v[138:141], v[170:173], v[126:129]
	v_mfma_f32_16x16x32_bf16 v[122:125], v[146:149], v[170:173], v[122:125]
	v_mfma_f32_16x16x32_bf16 v[110:113], v[138:141], v[178:181], v[110:113]
	v_mfma_f32_16x16x32_bf16 v[106:109], v[146:149], v[178:181], v[106:109]
	v_mfma_f32_16x16x32_bf16 v[94:97], v[138:141], v[190:193], v[94:97]
	v_mfma_f32_16x16x32_bf16 v[90:93], v[146:149], v[190:193], v[90:93]
	v_mfma_f32_16x16x32_bf16 v[78:81], v[138:141], v[198:201], v[78:81]
	v_mfma_f32_16x16x32_bf16 v[74:77], v[146:149], v[198:201], v[74:77]
	v_mfma_f32_16x16x32_bf16 v[126:129], v[142:145], v[174:177], v[126:129]
	v_mfma_f32_16x16x32_bf16 v[122:125], v[150:153], v[174:177], v[122:125]
	v_mfma_f32_16x16x32_bf16 v[110:113], v[142:145], v[182:185], v[110:113]
	v_mfma_f32_16x16x32_bf16 v[106:109], v[150:153], v[182:185], v[106:109]
	v_mfma_f32_16x16x32_bf16 v[94:97], v[142:145], v[194:197], v[94:97]
	v_mfma_f32_16x16x32_bf16 v[90:93], v[150:153], v[194:197], v[90:93]
	v_mfma_f32_16x16x32_bf16 v[78:81], v[142:145], v[214:217], v[78:81]
	v_mfma_f32_16x16x32_bf16 v[74:77], v[150:153], v[214:217], v[74:77]
	s_setprio 0
	s_setprio 1
	v_mfma_f32_16x16x32_bf16 v[118:121], v[154:157], v[170:173], v[118:121]
	v_mfma_f32_16x16x32_bf16 v[114:117], v[162:165], v[170:173], v[114:117]
	v_mfma_f32_16x16x32_bf16 v[102:105], v[154:157], v[178:181], v[102:105]
	v_mfma_f32_16x16x32_bf16 v[98:101], v[162:165], v[178:181], v[98:101]
	v_mfma_f32_16x16x32_bf16 v[86:89], v[154:157], v[190:193], v[86:89]
	v_mfma_f32_16x16x32_bf16 v[82:85], v[162:165], v[190:193], v[82:85]
	v_mfma_f32_16x16x32_bf16 v[70:73], v[154:157], v[198:201], v[70:73]
	v_mfma_f32_16x16x32_bf16 v[66:69], v[162:165], v[198:201], v[66:69]
	v_mfma_f32_16x16x32_bf16 v[118:121], v[158:161], v[174:177], v[118:121]
	v_mfma_f32_16x16x32_bf16 v[114:117], v[166:169], v[174:177], v[114:117]
	v_mfma_f32_16x16x32_bf16 v[102:105], v[158:161], v[182:185], v[102:105]
	v_mfma_f32_16x16x32_bf16 v[98:101], v[166:169], v[182:185], v[98:101]
	v_mfma_f32_16x16x32_bf16 v[86:89], v[158:161], v[194:197], v[86:89]
	v_mfma_f32_16x16x32_bf16 v[82:85], v[166:169], v[194:197], v[82:85]
	v_mfma_f32_16x16x32_bf16 v[70:73], v[158:161], v[214:217], v[70:73]
	v_mfma_f32_16x16x32_bf16 v[66:69], v[166:169], v[214:217], v[66:69]
	s_setprio 0
	s_barrier
	v_mov_b32_e32 v64, v133
	ds_read_b128 v[170:173], v137 offset:49152
	ds_read_b128 v[174:177], v137 offset:50176
	ds_read_b128 v[178:181], v137 offset:51200
	ds_read_b128 v[182:185], v137 offset:52224
	ds_read_b128 v[190:193], v137 offset:53248
	ds_read_b128 v[194:197], v137 offset:54272
	ds_read_b128 v[198:201], v137 offset:55296
	ds_read_b128 v[214:217], v137 offset:56320
	s_add_i32 s60, s70, s49
	v_lshl_add_u64 v[130:131], s[54:55], 0, v[64:65]
	v_lshl_add_u64 v[130:131], v[130:131], 0, s[24:25]
	s_mov_b32 m0, s60
	v_mov_b32_e32 v64, v135
	global_load_lds_dwordx4 v[130:131], off
	s_add_i32 m0, s60, 0x2000
	s_nop 0
	v_lshl_add_u64 v[130:131], s[54:55], 0, v[64:65]
	s_add_u32 s54, s54, 0x40080
	v_lshl_add_u64 v[130:131], v[130:131], 0, s[24:25]
	s_addc_u32 s55, s55, 0
	v_mov_b32_e32 v64, v133
	s_add_i32 s60, s71, s49
	global_load_lds_dwordx4 v[130:131], off
	s_mov_b32 m0, s60
	s_nop 0
	global_load_lds_dwordx4 v64, s[54:55]
	v_mov_b32_e32 v64, v135
	s_add_i32 m0, s60, 0x2000
	s_nop 0
	global_load_lds_dwordx4 v64, s[54:55]
	v_mov_b32_e32 v64, v132
	s_mov_b32 m0, s22
	v_lshl_add_u64 v[130:131], s[2:3], 0, v[64:65]
	v_lshl_add_u64 v[130:131], v[130:131], 0, s[24:25]
	v_mov_b32_e32 v64, v134
	global_load_lds_dwordx4 v[130:131], off
	s_mov_b32 m0, s56
	v_lshl_add_u64 v[130:131], s[2:3], 0, v[64:65]
	v_lshl_add_u64 v[130:131], v[130:131], 0, s[24:25]
	global_load_lds_dwordx4 v[130:131], off
	s_waitcnt vmcnt(8)
	s_waitcnt lgkmcnt(0)
	s_barrier
	s_setprio 1
	s_waitcnt lgkmcnt(0)
	v_mfma_f32_16x16x32_bf16 v[60:63], v[138:141], v[170:173], v[60:63]
	v_mfma_f32_16x16x32_bf16 v[56:59], v[146:149], v[170:173], v[56:59]
	v_mfma_f32_16x16x32_bf16 v[44:47], v[138:141], v[178:181], v[44:47]
	v_mfma_f32_16x16x32_bf16 v[40:43], v[146:149], v[178:181], v[40:43]
	v_mfma_f32_16x16x32_bf16 v[28:31], v[138:141], v[190:193], v[28:31]
	v_mfma_f32_16x16x32_bf16 v[24:27], v[146:149], v[190:193], v[24:27]
	v_mfma_f32_16x16x32_bf16 v[12:15], v[138:141], v[198:201], v[12:15]
	v_mfma_f32_16x16x32_bf16 v[8:11], v[146:149], v[198:201], v[8:11]
	v_mfma_f32_16x16x32_bf16 v[60:63], v[142:145], v[174:177], v[60:63]
	v_mfma_f32_16x16x32_bf16 v[56:59], v[150:153], v[174:177], v[56:59]
	v_mfma_f32_16x16x32_bf16 v[44:47], v[142:145], v[182:185], v[44:47]
	v_mfma_f32_16x16x32_bf16 v[40:43], v[150:153], v[182:185], v[40:43]
	v_mfma_f32_16x16x32_bf16 v[28:31], v[142:145], v[194:197], v[28:31]
	v_mfma_f32_16x16x32_bf16 v[24:27], v[150:153], v[194:197], v[24:27]
	v_mfma_f32_16x16x32_bf16 v[12:15], v[142:145], v[214:217], v[12:15]
	v_mfma_f32_16x16x32_bf16 v[8:11], v[150:153], v[214:217], v[8:11]
	s_setprio 0
	s_setprio 1
	v_mfma_f32_16x16x32_bf16 v[52:55], v[154:157], v[170:173], v[52:55]
	v_mfma_f32_16x16x32_bf16 v[48:51], v[162:165], v[170:173], v[48:51]
	v_mfma_f32_16x16x32_bf16 v[36:39], v[154:157], v[178:181], v[36:39]
	v_mfma_f32_16x16x32_bf16 v[32:35], v[162:165], v[178:181], v[32:35]
	v_mfma_f32_16x16x32_bf16 v[20:23], v[154:157], v[190:193], v[20:23]
	v_mfma_f32_16x16x32_bf16 v[16:19], v[162:165], v[190:193], v[16:19]
	v_mfma_f32_16x16x32_bf16 v[4:7], v[154:157], v[198:201], v[4:7]
	v_mfma_f32_16x16x32_bf16 v[0:3], v[162:165], v[198:201], v[0:3]
	v_mfma_f32_16x16x32_bf16 v[52:55], v[158:161], v[174:177], v[52:55]
	v_mfma_f32_16x16x32_bf16 v[48:51], v[166:169], v[174:177], v[48:51]
	v_mfma_f32_16x16x32_bf16 v[36:39], v[158:161], v[182:185], v[36:39]
	v_mfma_f32_16x16x32_bf16 v[32:35], v[166:169], v[182:185], v[32:35]
	v_mfma_f32_16x16x32_bf16 v[20:23], v[158:161], v[194:197], v[20:23]
	v_mfma_f32_16x16x32_bf16 v[16:19], v[166:169], v[194:197], v[16:19]
	v_mfma_f32_16x16x32_bf16 v[4:7], v[158:161], v[214:217], v[4:7]
	v_mfma_f32_16x16x32_bf16 v[0:3], v[166:169], v[214:217], v[0:3]
	s_setprio 0
	s_barrier
	s_add_i32 s69, s69, 2
	s_add_u32 s94, s94, 0x100
	s_addc_u32 s95, s95, 0
	s_add_u32 s67, s67, 0x100
	s_addc_u32 s68, s68, 0
	s_cmp_gt_u32 s69, 13
	s_cbranch_scc0 .LBB0_80
	s_and_b64 vcc, exec, s[80:81]
	s_cbranch_vccz .LBB0_83
	s_barrier

.LBB0_95:
	s_add_i32 s58, 0, 0x10000
	s_add_i32 s59, 0, 0x14000
	v_add_u32_e32 v64, s58, v134
	ds_read_b128 v[136:139], v64
	ds_read_b128 v[140:143], v64 offset:1024
	ds_read_b128 v[144:147], v64 offset:2048
	ds_read_b128 v[148:151], v64 offset:3072
	v_add_u32_e32 v64, s59, v134
	ds_read_b128 v[152:155], v64
	ds_read_b128 v[156:159], v64 offset:1024
	ds_read_b128 v[160:163], v64 offset:2048
	ds_read_b128 v[164:167], v64 offset:3072
	s_add_u32 s2, s84, 0xf3ac0080
	s_addc_u32 s3, s85, -1
	s_cmp_lg_u32 s53, 12
	s_cselect_b32 s54, s2, 0
	s_cselect_b32 s55, s3, 0
	s_add_u32 s2, s82, s54
	s_addc_u32 s3, s83, s55
	s_add_u32 s54, s46, s54
	s_addc_u32 s55, s47, s55
	s_add_i32 m0, s10, 0xc000
	v_mov_b32_e32 v64, v130
	s_add_u32 s56, s51, s84
	ds_read_b128 v[168:171], v135
	ds_read_b128 v[172:175], v135 offset:1024
	ds_read_b128 v[176:179], v135 offset:2048
	ds_read_b128 v[180:183], v135 offset:3072
	ds_read_b128 v[184:187], v135 offset:4096
	ds_read_b128 v[190:193], v135 offset:5120
	ds_read_b128 v[194:197], v135 offset:6144
	ds_read_b128 v[198:201], v135 offset:7168
	s_addc_u32 s57, s52, s85
	global_load_lds_dwordx4 v64, s[56:57]
	v_mov_b32_e32 v64, v132
	s_add_i32 m0, s10, 0xe000
	s_nop 0
	global_load_lds_dwordx4 v64, s[56:57]
	s_waitcnt vmcnt(8)
	s_waitcnt lgkmcnt(0)
	s_barrier
	s_setprio 1
	s_waitcnt lgkmcnt(0)
	v_mfma_f32_16x16x32_bf16 v[52:55], v[136:139], v[168:171], v[52:55]
	v_mfma_f32_16x16x32_bf16 v[48:51], v[144:147], v[168:171], v[48:51]
	v_mfma_f32_16x16x32_bf16 v[4:7], v[136:139], v[176:179], v[4:7]
	v_mfma_f32_16x16x32_bf16 v[0:3], v[144:147], v[176:179], v[0:3]
	v_mfma_f32_16x16x32_bf16 v[36:39], v[136:139], v[184:187], v[36:39]
	v_mfma_f32_16x16x32_bf16 v[32:35], v[144:147], v[184:187], v[32:35]
	v_mfma_f32_16x16x32_bf16 v[78:81], v[136:139], v[194:197], v[78:81]
	v_mfma_f32_16x16x32_bf16 v[74:77], v[144:147], v[194:197], v[74:77]
	v_mfma_f32_16x16x32_bf16 v[52:55], v[140:143], v[172:175], v[52:55]
	v_mfma_f32_16x16x32_bf16 v[48:51], v[148:151], v[172:175], v[48:51]
	v_mfma_f32_16x16x32_bf16 v[4:7], v[140:143], v[180:183], v[4:7]
	v_mfma_f32_16x16x32_bf16 v[0:3], v[148:151], v[180:183], v[0:3]
	v_mfma_f32_16x16x32_bf16 v[36:39], v[140:143], v[190:193], v[36:39]
	v_mfma_f32_16x16x32_bf16 v[32:35], v[148:151], v[190:193], v[32:35]
	v_mfma_f32_16x16x32_bf16 v[78:81], v[140:143], v[198:201], v[78:81]
	v_mfma_f32_16x16x32_bf16 v[74:77], v[148:151], v[198:201], v[74:77]
	s_setprio 0
	s_setprio 1
	v_mfma_f32_16x16x32_bf16 v[24:27], v[152:155], v[168:171], v[24:27]
	v_mfma_f32_16x16x32_bf16 v[20:23], v[160:163], v[168:171], v[20:23]
	v_mfma_f32_16x16x32_bf16 v[12:15], v[152:155], v[176:179], v[12:15]
	v_mfma_f32_16x16x32_bf16 v[28:31], v[160:163], v[176:179], v[28:31]
	v_mfma_f32_16x16x32_bf16 v[56:59], v[152:155], v[184:187], v[56:59]
	v_mfma_f32_16x16x32_bf16 v[66:69], v[160:163], v[184:187], v[66:69]
	v_mfma_f32_16x16x32_bf16 v[86:89], v[152:155], v[194:197], v[86:89]
	v_mfma_f32_16x16x32_bf16 v[94:97], v[160:163], v[194:197], v[94:97]
	v_mfma_f32_16x16x32_bf16 v[24:27], v[156:159], v[172:175], v[24:27]
	v_mfma_f32_16x16x32_bf16 v[20:23], v[164:167], v[172:175], v[20:23]
	v_mfma_f32_16x16x32_bf16 v[12:15], v[156:159], v[180:183], v[12:15]
	v_mfma_f32_16x16x32_bf16 v[28:31], v[164:167], v[180:183], v[28:31]
	v_mfma_f32_16x16x32_bf16 v[56:59], v[156:159], v[190:193], v[56:59]
	v_mfma_f32_16x16x32_bf16 v[66:69], v[164:167], v[190:193], v[66:69]
	v_mfma_f32_16x16x32_bf16 v[86:89], v[156:159], v[198:201], v[86:89]
	v_mfma_f32_16x16x32_bf16 v[94:97], v[164:167], v[198:201], v[94:97]
	s_setprio 0
	s_barrier
	v_mov_b32_e32 v64, v131
	s_add_i32 s56, s58, s7
	ds_read_b128 v[168:171], v135 offset:16384
	ds_read_b128 v[172:175], v135 offset:17408
	ds_read_b128 v[176:179], v135 offset:18432
	ds_read_b128 v[180:183], v135 offset:19456
	ds_read_b128 v[184:187], v135 offset:20480
	ds_read_b128 v[190:193], v135 offset:21504
	ds_read_b128 v[194:197], v135 offset:22528
	ds_read_b128 v[198:201], v135 offset:23552
	s_mov_b32 m0, s56
	s_nop 0
	global_load_lds_dwordx4 v64, s[54:55]
	v_mov_b32_e32 v64, v133
	s_add_i32 m0, s56, 0x2000
	s_add_u32 s56, s54, 0x40000
	global_load_lds_dwordx4 v64, s[54:55]
	s_addc_u32 s57, s55, 0
	v_mov_b32_e32 v64, v131
	s_add_i32 s58, s59, s7
	s_mov_b32 m0, s58
	s_nop 0
	global_load_lds_dwordx4 v64, s[56:57]
	v_mov_b32_e32 v64, v133
	s_add_i32 m0, s58, 0x2000
	s_nop 0
	global_load_lds_dwordx4 v64, s[56:57]
	v_mov_b32_e32 v64, v130
	s_mov_b32 m0, s10
	s_nop 0
	global_load_lds_dwordx4 v64, s[2:3]
	v_mov_b32_e32 v64, v132
	s_mov_b32 m0, s17
	s_nop 0
	global_load_lds_dwordx4 v64, s[2:3]
	s_waitcnt vmcnt(8)
	s_waitcnt lgkmcnt(0)
	s_barrier
	s_setprio 1
	s_waitcnt lgkmcnt(0)
	v_mfma_f32_16x16x32_bf16 v[106:109], v[136:139], v[168:171], v[106:109]
	v_mfma_f32_16x16x32_bf16 v[102:105], v[144:147], v[168:171], v[102:105]
	v_mfma_f32_16x16x32_bf16 v[126:129], v[136:139], v[176:179], v[126:129]
	v_mfma_f32_16x16x32_bf16 v[122:125], v[144:147], v[176:179], v[122:125]
	v_mfma_f32_16x16x32_bf16 v[90:93], v[136:139], v[184:187], v[90:93]
	v_mfma_f32_16x16x32_bf16 v[82:85], v[144:147], v[184:187], v[82:85]
	v_mfma_f32_16x16x32_bf16 v[44:47], v[136:139], v[194:197], v[44:47]
	v_mfma_f32_16x16x32_bf16 v[40:43], v[144:147], v[194:197], v[40:43]
	v_mfma_f32_16x16x32_bf16 v[106:109], v[140:143], v[172:175], v[106:109]
	v_mfma_f32_16x16x32_bf16 v[102:105], v[148:151], v[172:175], v[102:105]
	v_mfma_f32_16x16x32_bf16 v[126:129], v[140:143], v[180:183], v[126:129]
	v_mfma_f32_16x16x32_bf16 v[122:125], v[148:151], v[180:183], v[122:125]
	v_mfma_f32_16x16x32_bf16 v[90:93], v[140:143], v[190:193], v[90:93]
	v_mfma_f32_16x16x32_bf16 v[82:85], v[148:151], v[190:193], v[82:85]
	v_mfma_f32_16x16x32_bf16 v[44:47], v[140:143], v[198:201], v[44:47]
	v_mfma_f32_16x16x32_bf16 v[40:43], v[148:151], v[198:201], v[40:43]
	s_setprio 0
	s_setprio 1
	v_mfma_f32_16x16x32_bf16 v[114:117], v[152:155], v[168:171], v[114:117]
	v_mfma_f32_16x16x32_bf16 v[118:121], v[160:163], v[168:171], v[118:121]
	v_mfma_f32_16x16x32_bf16 v[110:113], v[152:155], v[176:179], v[110:113]
	v_mfma_f32_16x16x32_bf16 v[98:101], v[160:163], v[176:179], v[98:101]
	v_mfma_f32_16x16x32_bf16 v[70:73], v[152:155], v[184:187], v[70:73]
	v_mfma_f32_16x16x32_bf16 v[60:63], v[160:163], v[184:187], v[60:63]
	v_mfma_f32_16x16x32_bf16 v[16:19], v[152:155], v[194:197], v[16:19]
	v_mfma_f32_16x16x32_bf16 v[8:11], v[160:163], v[194:197], v[8:11]
	v_mfma_f32_16x16x32_bf16 v[114:117], v[156:159], v[172:175], v[114:117]
	v_mfma_f32_16x16x32_bf16 v[118:121], v[164:167], v[172:175], v[118:121]
	v_mfma_f32_16x16x32_bf16 v[110:113], v[156:159], v[180:183], v[110:113]
	v_mfma_f32_16x16x32_bf16 v[98:101], v[164:167], v[180:183], v[98:101]
	v_mfma_f32_16x16x32_bf16 v[70:73], v[156:159], v[190:193], v[70:73]
	v_mfma_f32_16x16x32_bf16 v[60:63], v[164:167], v[190:193], v[60:63]
	v_mfma_f32_16x16x32_bf16 v[16:19], v[156:159], v[198:201], v[16:19]
	v_mfma_f32_16x16x32_bf16 v[8:11], v[164:167], v[198:201], v[8:11]
	s_setprio 0
	s_barrier
	s_add_i32 s58, 0, 0x18000
	v_add_u32_e32 v64, s58, v134
	s_add_i32 s59, 0, 0x1c000
	ds_read_b128 v[136:139], v64
	ds_read_b128 v[140:143], v64 offset:1024
	ds_read_b128 v[144:147], v64 offset:2048
	ds_read_b128 v[148:151], v64 offset:3072
	v_add_u32_e32 v64, s59, v134
	ds_read_b128 v[152:155], v64
	ds_read_b128 v[156:159], v64 offset:1024
	ds_read_b128 v[160:163], v64 offset:2048
	ds_read_b128 v[164:167], v64 offset:3072
	s_add_u32 s56, s2, 0x40000
	v_mov_b32_e32 v64, v130
	s_mov_b32 m0, s22
	ds_read_b128 v[168:171], v135 offset:32768
	ds_read_b128 v[172:175], v135 offset:33792
	ds_read_b128 v[176:179], v135 offset:34816
	ds_read_b128 v[180:183], v135 offset:35840
	ds_read_b128 v[184:187], v135 offset:36864
	ds_read_b128 v[190:193], v135 offset:37888
	ds_read_b128 v[194:197], v135 offset:38912
	ds_read_b128 v[198:201], v135 offset:39936
	s_addc_u32 s57, s3, 0
	s_nop 0
	global_load_lds_dwordx4 v64, s[56:57]
	v_mov_b32_e32 v64, v132
	s_mov_b32 m0, s41
	s_nop 0
	global_load_lds_dwordx4 v64, s[56:57]
	s_waitcnt vmcnt(8)
	s_waitcnt lgkmcnt(0)
	s_barrier
	s_setprio 1
	s_waitcnt lgkmcnt(0)
	v_mfma_f32_16x16x32_bf16 v[52:55], v[136:139], v[168:171], v[52:55]
	v_mfma_f32_16x16x32_bf16 v[48:51], v[144:147], v[168:171], v[48:51]
	v_mfma_f32_16x16x32_bf16 v[4:7], v[136:139], v[176:179], v[4:7]
	v_mfma_f32_16x16x32_bf16 v[0:3], v[144:147], v[176:179], v[0:3]
	v_mfma_f32_16x16x32_bf16 v[36:39], v[136:139], v[184:187], v[36:39]
	v_mfma_f32_16x16x32_bf16 v[32:35], v[144:147], v[184:187], v[32:35]
	v_mfma_f32_16x16x32_bf16 v[78:81], v[136:139], v[194:197], v[78:81]
	v_mfma_f32_16x16x32_bf16 v[74:77], v[144:147], v[194:197], v[74:77]
	v_mfma_f32_16x16x32_bf16 v[52:55], v[140:143], v[172:175], v[52:55]
	v_mfma_f32_16x16x32_bf16 v[48:51], v[148:151], v[172:175], v[48:51]
	v_mfma_f32_16x16x32_bf16 v[4:7], v[140:143], v[180:183], v[4:7]
	v_mfma_f32_16x16x32_bf16 v[0:3], v[148:151], v[180:183], v[0:3]
	v_mfma_f32_16x16x32_bf16 v[36:39], v[140:143], v[190:193], v[36:39]
	v_mfma_f32_16x16x32_bf16 v[32:35], v[148:151], v[190:193], v[32:35]
	v_mfma_f32_16x16x32_bf16 v[78:81], v[140:143], v[198:201], v[78:81]
	v_mfma_f32_16x16x32_bf16 v[74:77], v[148:151], v[198:201], v[74:77]
	s_setprio 0
	s_setprio 1
	v_mfma_f32_16x16x32_bf16 v[24:27], v[152:155], v[168:171], v[24:27]
	v_mfma_f32_16x16x32_bf16 v[20:23], v[160:163], v[168:171], v[20:23]
	v_mfma_f32_16x16x32_bf16 v[12:15], v[152:155], v[176:179], v[12:15]
	v_mfma_f32_16x16x32_bf16 v[28:31], v[160:163], v[176:179], v[28:31]
	v_mfma_f32_16x16x32_bf16 v[56:59], v[152:155], v[184:187], v[56:59]
	v_mfma_f32_16x16x32_bf16 v[66:69], v[160:163], v[184:187], v[66:69]
	v_mfma_f32_16x16x32_bf16 v[86:89], v[152:155], v[194:197], v[86:89]
	v_mfma_f32_16x16x32_bf16 v[94:97], v[160:163], v[194:197], v[94:97]
	v_mfma_f32_16x16x32_bf16 v[24:27], v[156:159], v[172:175], v[24:27]
	v_mfma_f32_16x16x32_bf16 v[20:23], v[164:167], v[172:175], v[20:23]
	v_mfma_f32_16x16x32_bf16 v[12:15], v[156:159], v[180:183], v[12:15]
	v_mfma_f32_16x16x32_bf16 v[28:31], v[164:167], v[180:183], v[28:31]
	v_mfma_f32_16x16x32_bf16 v[56:59], v[156:159], v[190:193], v[56:59]
	v_mfma_f32_16x16x32_bf16 v[66:69], v[164:167], v[190:193], v[66:69]
	v_mfma_f32_16x16x32_bf16 v[86:89], v[156:159], v[198:201], v[86:89]
	v_mfma_f32_16x16x32_bf16 v[94:97], v[164:167], v[198:201], v[94:97]
	s_setprio 0
	s_barrier
	v_mov_b32_e32 v64, v131
	ds_read_b128 v[168:171], v135 offset:49152
	ds_read_b128 v[172:175], v135 offset:50176
	ds_read_b128 v[176:179], v135 offset:51200
	ds_read_b128 v[180:183], v135 offset:52224
	ds_read_b128 v[184:187], v135 offset:53248
	ds_read_b128 v[190:193], v135 offset:54272
	ds_read_b128 v[194:197], v135 offset:55296
	ds_read_b128 v[198:201], v135 offset:56320
	s_add_i32 s56, s58, s7
	v_lshl_add_u64 v[214:215], s[54:55], 0, v[64:65]
	v_lshl_add_u64 v[214:215], v[214:215], 0, s[24:25]
	s_mov_b32 m0, s56
	v_mov_b32_e32 v64, v133
	global_load_lds_dwordx4 v[214:215], off
	s_add_i32 m0, s56, 0x2000
	s_nop 0
	v_lshl_add_u64 v[214:215], s[54:55], 0, v[64:65]
	s_add_u32 s54, s54, 0x40080
	v_lshl_add_u64 v[214:215], v[214:215], 0, s[24:25]
	s_addc_u32 s55, s55, 0
	v_mov_b32_e32 v64, v131
	s_add_i32 s56, s59, s7
	global_load_lds_dwordx4 v[214:215], off
	s_mov_b32 m0, s56
	s_nop 0
	global_load_lds_dwordx4 v64, s[54:55]
	v_mov_b32_e32 v64, v133
	s_add_i32 m0, s56, 0x2000
	s_nop 0
	global_load_lds_dwordx4 v64, s[54:55]
	v_mov_b32_e32 v64, v130
	s_mov_b32 m0, s49
	v_lshl_add_u64 v[214:215], s[2:3], 0, v[64:65]
	v_lshl_add_u64 v[214:215], v[214:215], 0, s[24:25]
	v_mov_b32_e32 v64, v132
	global_load_lds_dwordx4 v[214:215], off
	s_mov_b32 m0, s50
	v_lshl_add_u64 v[214:215], s[2:3], 0, v[64:65]
	v_lshl_add_u64 v[214:215], v[214:215], 0, s[24:25]
	global_load_lds_dwordx4 v[214:215], off
	s_waitcnt vmcnt(8)
	s_waitcnt lgkmcnt(0)
	s_barrier
	s_setprio 1
	s_waitcnt lgkmcnt(0)
	v_mfma_f32_16x16x32_bf16 v[106:109], v[136:139], v[168:171], v[106:109]
	v_mfma_f32_16x16x32_bf16 v[102:105], v[144:147], v[168:171], v[102:105]
	v_mfma_f32_16x16x32_bf16 v[126:129], v[136:139], v[176:179], v[126:129]
	v_mfma_f32_16x16x32_bf16 v[122:125], v[144:147], v[176:179], v[122:125]
	v_mfma_f32_16x16x32_bf16 v[90:93], v[136:139], v[184:187], v[90:93]
	v_mfma_f32_16x16x32_bf16 v[82:85], v[144:147], v[184:187], v[82:85]
	v_mfma_f32_16x16x32_bf16 v[44:47], v[136:139], v[194:197], v[44:47]
	v_mfma_f32_16x16x32_bf16 v[40:43], v[144:147], v[194:197], v[40:43]
	v_mfma_f32_16x16x32_bf16 v[106:109], v[140:143], v[172:175], v[106:109]
	v_mfma_f32_16x16x32_bf16 v[102:105], v[148:151], v[172:175], v[102:105]
	v_mfma_f32_16x16x32_bf16 v[126:129], v[140:143], v[180:183], v[126:129]
	v_mfma_f32_16x16x32_bf16 v[122:125], v[148:151], v[180:183], v[122:125]
	v_mfma_f32_16x16x32_bf16 v[90:93], v[140:143], v[190:193], v[90:93]
	v_mfma_f32_16x16x32_bf16 v[82:85], v[148:151], v[190:193], v[82:85]
	v_mfma_f32_16x16x32_bf16 v[44:47], v[140:143], v[198:201], v[44:47]
	v_mfma_f32_16x16x32_bf16 v[40:43], v[148:151], v[198:201], v[40:43]
	s_setprio 0
	s_setprio 1
	v_mfma_f32_16x16x32_bf16 v[114:117], v[152:155], v[168:171], v[114:117]
	v_mfma_f32_16x16x32_bf16 v[118:121], v[160:163], v[168:171], v[118:121]
	v_mfma_f32_16x16x32_bf16 v[110:113], v[152:155], v[176:179], v[110:113]
	v_mfma_f32_16x16x32_bf16 v[98:101], v[160:163], v[176:179], v[98:101]
	v_mfma_f32_16x16x32_bf16 v[70:73], v[152:155], v[184:187], v[70:73]
	v_mfma_f32_16x16x32_bf16 v[60:63], v[160:163], v[184:187], v[60:63]
	v_mfma_f32_16x16x32_bf16 v[16:19], v[152:155], v[194:197], v[16:19]
	v_mfma_f32_16x16x32_bf16 v[8:11], v[160:163], v[194:197], v[8:11]
	v_mfma_f32_16x16x32_bf16 v[114:117], v[156:159], v[172:175], v[114:117]
	v_mfma_f32_16x16x32_bf16 v[118:121], v[164:167], v[172:175], v[118:121]
	v_mfma_f32_16x16x32_bf16 v[110:113], v[156:159], v[180:183], v[110:113]
	v_mfma_f32_16x16x32_bf16 v[98:101], v[164:167], v[180:183], v[98:101]
	v_mfma_f32_16x16x32_bf16 v[70:73], v[156:159], v[190:193], v[70:73]
	v_mfma_f32_16x16x32_bf16 v[60:63], v[164:167], v[190:193], v[60:63]
	v_mfma_f32_16x16x32_bf16 v[16:19], v[156:159], v[198:201], v[16:19]
	v_mfma_f32_16x16x32_bf16 v[8:11], v[164:167], v[198:201], v[8:11]
	s_setprio 0
	s_barrier
	s_add_i32 s53, s53, 2
	s_add_u32 s84, s84, 0x100
	s_addc_u32 s85, s85, 0
	s_cmp_gt_u32 s53, 13
	s_cbranch_scc0 .LBB0_95
	s_cmp_lt_u32 s48, 4
	s_cbranch_scc0 .LBB0_98
	s_barrier

.LBB0_145:
	s_add_i32 s87, 0, 0x10000
	s_add_i32 s85, 0, 0x14000
	v_add_u32_e32 v64, s87, v196
	ds_read_b128 v[132:135], v64
	ds_read_b128 v[136:139], v64 offset:1024
	ds_read_b128 v[140:143], v64 offset:2048
	ds_read_b128 v[144:147], v64 offset:3072
	v_add_u32_e32 v64, s85, v196
	ds_read_b128 v[148:151], v64
	ds_read_b128 v[152:155], v64 offset:1024
	ds_read_b128 v[156:159], v64 offset:2048
	ds_read_b128 v[160:163], v64 offset:3072
	s_add_i32 s77, s77, 2
	s_cmp_gt_u32 s77, 5
	s_cselect_b32 s2, 0xffc00, 0
	s_add_u32 s60, s92, s94
	s_addc_u32 s61, s93, s95
	s_add_u32 s54, s60, 0x100
	s_addc_u32 s3, s61, 0
	s_add_u32 s2, s2, s94
	s_addc_u32 s55, 0, s95
	s_add_u32 s85, s71, s2
	s_addc_u32 s55, s76, s55
	s_cmpk_eq_i32 s94, 0x700
	s_cselect_b32 s3, s64, s3
	s_cselect_b32 s2, s65, s54
	s_cselect_b32 s55, s68, s55
	s_cselect_b32 s54, s69, s85
	s_add_i32 s85, 0, 0x14000
	v_mov_b32_e32 v64, v192
	ds_read_b128 v[164:167], v197
	ds_read_b128 v[168:171], v197 offset:1024
	ds_read_b128 v[172:175], v197 offset:2048
	ds_read_b128 v[176:179], v197 offset:3072
	ds_read_b128 v[180:183], v197 offset:4096
	ds_read_b128 v[184:187], v197 offset:5120
	ds_read_b128 v[198:201], v197 offset:6144
	ds_read_b128 v[214:217], v197 offset:7168
	s_add_i32 m0, s50, 0xc000
	v_lshl_add_u64 v[66:67], s[60:61], 0, v[64:65]
	v_lshl_add_u64 v[66:67], v[66:67], 0, s[34:35]
	v_mov_b32_e32 v64, v194
	global_load_lds_dwordx4 v[66:67], off
	s_add_i32 m0, s50, 0xe000
	v_lshl_add_u64 v[66:67], s[60:61], 0, v[64:65]
	v_lshl_add_u64 v[66:67], v[66:67], 0, s[34:35]
	global_load_lds_dwordx4 v[66:67], off
	s_waitcnt vmcnt(8)
	s_waitcnt lgkmcnt(0)
	s_barrier
	s_setprio 1
	s_waitcnt lgkmcnt(0)
	v_mfma_f32_16x16x32_bf16 v[128:131], v[132:135], v[164:167], v[128:131]
	v_mfma_f32_16x16x32_bf16 v[124:127], v[140:143], v[164:167], v[124:127]
	v_mfma_f32_16x16x32_bf16 v[112:115], v[132:135], v[172:175], v[112:115]
	v_mfma_f32_16x16x32_bf16 v[108:111], v[140:143], v[172:175], v[108:111]
	v_mfma_f32_16x16x32_bf16 v[96:99], v[132:135], v[180:183], v[96:99]
	v_mfma_f32_16x16x32_bf16 v[92:95], v[140:143], v[180:183], v[92:95]
	v_mfma_f32_16x16x32_bf16 v[80:83], v[132:135], v[198:201], v[80:83]
	v_mfma_f32_16x16x32_bf16 v[76:79], v[140:143], v[198:201], v[76:79]
	v_mfma_f32_16x16x32_bf16 v[128:131], v[136:139], v[168:171], v[128:131]
	v_mfma_f32_16x16x32_bf16 v[124:127], v[144:147], v[168:171], v[124:127]
	v_mfma_f32_16x16x32_bf16 v[112:115], v[136:139], v[176:179], v[112:115]
	v_mfma_f32_16x16x32_bf16 v[108:111], v[144:147], v[176:179], v[108:111]
	v_mfma_f32_16x16x32_bf16 v[96:99], v[136:139], v[184:187], v[96:99]
	v_mfma_f32_16x16x32_bf16 v[92:95], v[144:147], v[184:187], v[92:95]
	v_mfma_f32_16x16x32_bf16 v[80:83], v[136:139], v[214:217], v[80:83]
	v_mfma_f32_16x16x32_bf16 v[76:79], v[144:147], v[214:217], v[76:79]
	s_setprio 0
	s_setprio 1
	v_mfma_f32_16x16x32_bf16 v[120:123], v[148:151], v[164:167], v[120:123]
	v_mfma_f32_16x16x32_bf16 v[116:119], v[156:159], v[164:167], v[116:119]
	v_mfma_f32_16x16x32_bf16 v[104:107], v[148:151], v[172:175], v[104:107]
	v_mfma_f32_16x16x32_bf16 v[100:103], v[156:159], v[172:175], v[100:103]
	v_mfma_f32_16x16x32_bf16 v[88:91], v[148:151], v[180:183], v[88:91]
	v_mfma_f32_16x16x32_bf16 v[84:87], v[156:159], v[180:183], v[84:87]
	v_mfma_f32_16x16x32_bf16 v[72:75], v[148:151], v[198:201], v[72:75]
	v_mfma_f32_16x16x32_bf16 v[66:69], v[156:159], v[198:201], v[68:71]
	v_mfma_f32_16x16x32_bf16 v[120:123], v[152:155], v[168:171], v[120:123]
	v_mfma_f32_16x16x32_bf16 v[116:119], v[160:163], v[168:171], v[116:119]
	v_mfma_f32_16x16x32_bf16 v[104:107], v[152:155], v[176:179], v[104:107]
	v_mfma_f32_16x16x32_bf16 v[100:103], v[160:163], v[176:179], v[100:103]
	v_mfma_f32_16x16x32_bf16 v[88:91], v[152:155], v[184:187], v[88:91]
	v_mfma_f32_16x16x32_bf16 v[84:87], v[160:163], v[184:187], v[84:87]
	v_mfma_f32_16x16x32_bf16 v[72:75], v[152:155], v[214:217], v[72:75]
	v_mfma_f32_16x16x32_bf16 v[66:69], v[160:163], v[214:217], v[66:69]
	s_setprio 0
	s_barrier
	v_mov_b32_e32 v64, v193
	s_add_i32 s60, s87, s49
	ds_read_b128 v[164:167], v197 offset:16384
	ds_read_b128 v[168:171], v197 offset:17408
	ds_read_b128 v[172:175], v197 offset:18432
	ds_read_b128 v[176:179], v197 offset:19456
	ds_read_b128 v[180:183], v197 offset:20480
	ds_read_b128 v[184:187], v197 offset:21504
	ds_read_b128 v[198:201], v197 offset:22528
	ds_read_b128 v[214:217], v197 offset:23552
	s_mov_b32 m0, s60
	s_nop 0
	global_load_lds_dwordx4 v64, s[54:55]
	v_mov_b32_e32 v64, v195
	s_add_i32 m0, s60, 0x2000
	s_add_u32 s60, s54, 0x20000
	global_load_lds_dwordx4 v64, s[54:55]
	s_addc_u32 s61, s55, 0
	v_mov_b32_e32 v64, v193
	s_add_i32 s85, s85, s49
	s_mov_b32 m0, s85
	s_nop 0
	global_load_lds_dwordx4 v64, s[60:61]
	v_mov_b32_e32 v64, v195
	s_add_i32 m0, s85, 0x2000
	s_nop 0
	global_load_lds_dwordx4 v64, s[60:61]
	v_mov_b32_e32 v64, v192
	s_mov_b32 m0, s50
	s_nop 0
	global_load_lds_dwordx4 v64, s[2:3]
	v_mov_b32_e32 v64, v194
	s_mov_b32 m0, s51
	s_nop 0
	global_load_lds_dwordx4 v64, s[2:3]
	s_waitcnt vmcnt(8)
	s_waitcnt lgkmcnt(0)
	s_barrier
	s_setprio 1
	s_waitcnt lgkmcnt(0)
	v_mfma_f32_16x16x32_bf16 v[60:63], v[132:135], v[164:167], v[60:63]
	v_mfma_f32_16x16x32_bf16 v[56:59], v[140:143], v[164:167], v[56:59]
	v_mfma_f32_16x16x32_bf16 v[44:47], v[132:135], v[172:175], v[44:47]
	v_mfma_f32_16x16x32_bf16 v[40:43], v[140:143], v[172:175], v[40:43]
	v_mfma_f32_16x16x32_bf16 v[28:31], v[132:135], v[180:183], v[28:31]
	v_mfma_f32_16x16x32_bf16 v[24:27], v[140:143], v[180:183], v[24:27]
	v_mfma_f32_16x16x32_bf16 v[12:15], v[132:135], v[198:201], v[12:15]
	v_mfma_f32_16x16x32_bf16 v[8:11], v[140:143], v[198:201], v[8:11]
	v_mfma_f32_16x16x32_bf16 v[60:63], v[136:139], v[168:171], v[60:63]
	v_mfma_f32_16x16x32_bf16 v[56:59], v[144:147], v[168:171], v[56:59]
	v_mfma_f32_16x16x32_bf16 v[44:47], v[136:139], v[176:179], v[44:47]
	v_mfma_f32_16x16x32_bf16 v[40:43], v[144:147], v[176:179], v[40:43]
	v_mfma_f32_16x16x32_bf16 v[28:31], v[136:139], v[184:187], v[28:31]
	v_mfma_f32_16x16x32_bf16 v[24:27], v[144:147], v[184:187], v[24:27]
	v_mfma_f32_16x16x32_bf16 v[12:15], v[136:139], v[214:217], v[12:15]
	v_mfma_f32_16x16x32_bf16 v[8:11], v[144:147], v[214:217], v[8:11]
	s_setprio 0
	s_setprio 1
	v_mfma_f32_16x16x32_bf16 v[52:55], v[148:151], v[164:167], v[52:55]
	v_mfma_f32_16x16x32_bf16 v[48:51], v[156:159], v[164:167], v[48:51]
	v_mfma_f32_16x16x32_bf16 v[36:39], v[148:151], v[172:175], v[36:39]
	v_mfma_f32_16x16x32_bf16 v[32:35], v[156:159], v[172:175], v[32:35]
	v_mfma_f32_16x16x32_bf16 v[20:23], v[148:151], v[180:183], v[20:23]
	v_mfma_f32_16x16x32_bf16 v[16:19], v[156:159], v[180:183], v[16:19]
	v_mfma_f32_16x16x32_bf16 v[4:7], v[148:151], v[198:201], v[4:7]
	v_mfma_f32_16x16x32_bf16 v[0:3], v[156:159], v[198:201], v[0:3]
	v_mfma_f32_16x16x32_bf16 v[52:55], v[152:155], v[168:171], v[52:55]
	v_mfma_f32_16x16x32_bf16 v[48:51], v[160:163], v[168:171], v[48:51]
	v_mfma_f32_16x16x32_bf16 v[36:39], v[152:155], v[176:179], v[36:39]
	v_mfma_f32_16x16x32_bf16 v[32:35], v[160:163], v[176:179], v[32:35]
	v_mfma_f32_16x16x32_bf16 v[20:23], v[152:155], v[184:187], v[20:23]
	v_mfma_f32_16x16x32_bf16 v[16:19], v[160:163], v[184:187], v[16:19]
	v_mfma_f32_16x16x32_bf16 v[4:7], v[152:155], v[214:217], v[4:7]
	v_mfma_f32_16x16x32_bf16 v[0:3], v[160:163], v[214:217], v[0:3]
	s_setprio 0
	s_barrier
	s_add_i32 s85, 0, 0x18000
	v_add_u32_e32 v64, s85, v196
	s_add_i32 s87, 0, 0x1c000
	ds_read_b128 v[132:135], v64
	ds_read_b128 v[136:139], v64 offset:1024
	ds_read_b128 v[140:143], v64 offset:2048
	ds_read_b128 v[144:147], v64 offset:3072
	v_add_u32_e32 v64, s87, v196
	ds_read_b128 v[148:151], v64
	ds_read_b128 v[152:155], v64 offset:1024
	ds_read_b128 v[156:159], v64 offset:2048
	ds_read_b128 v[160:163], v64 offset:3072
	s_add_u32 s60, s2, 0x40000
	v_mov_b32_e32 v64, v192
	s_mov_b32 m0, s52
	ds_read_b128 v[164:167], v197 offset:32768
	ds_read_b128 v[168:171], v197 offset:33792
	ds_read_b128 v[172:175], v197 offset:34816
	ds_read_b128 v[176:179], v197 offset:35840
	ds_read_b128 v[180:183], v197 offset:36864
	ds_read_b128 v[184:187], v197 offset:37888
	ds_read_b128 v[198:201], v197 offset:38912
	ds_read_b128 v[214:217], v197 offset:39936
	s_addc_u32 s61, s3, 0
	s_nop 0
	global_load_lds_dwordx4 v64, s[60:61]
	v_mov_b32_e32 v64, v194
	s_mov_b32 m0, s53
	s_nop 0
	global_load_lds_dwordx4 v64, s[60:61]
	s_waitcnt vmcnt(8)
	s_waitcnt lgkmcnt(0)
	s_barrier
	s_setprio 1
	s_waitcnt lgkmcnt(0)
	v_mfma_f32_16x16x32_bf16 v[128:131], v[132:135], v[164:167], v[128:131]
	v_mfma_f32_16x16x32_bf16 v[124:127], v[140:143], v[164:167], v[124:127]
	v_mfma_f32_16x16x32_bf16 v[112:115], v[132:135], v[172:175], v[112:115]
	v_mfma_f32_16x16x32_bf16 v[108:111], v[140:143], v[172:175], v[108:111]
	v_mfma_f32_16x16x32_bf16 v[96:99], v[132:135], v[180:183], v[96:99]
	v_mfma_f32_16x16x32_bf16 v[92:95], v[140:143], v[180:183], v[92:95]
	v_mfma_f32_16x16x32_bf16 v[80:83], v[132:135], v[198:201], v[80:83]
	v_mfma_f32_16x16x32_bf16 v[76:79], v[140:143], v[198:201], v[76:79]
	v_mfma_f32_16x16x32_bf16 v[128:131], v[136:139], v[168:171], v[128:131]
	v_mfma_f32_16x16x32_bf16 v[124:127], v[144:147], v[168:171], v[124:127]
	v_mfma_f32_16x16x32_bf16 v[112:115], v[136:139], v[176:179], v[112:115]
	v_mfma_f32_16x16x32_bf16 v[108:111], v[144:147], v[176:179], v[108:111]
	v_mfma_f32_16x16x32_bf16 v[96:99], v[136:139], v[184:187], v[96:99]
	v_mfma_f32_16x16x32_bf16 v[92:95], v[144:147], v[184:187], v[92:95]
	v_mfma_f32_16x16x32_bf16 v[80:83], v[136:139], v[214:217], v[80:83]
	v_mfma_f32_16x16x32_bf16 v[76:79], v[144:147], v[214:217], v[76:79]
	s_setprio 0
	s_setprio 1
	v_mfma_f32_16x16x32_bf16 v[120:123], v[148:151], v[164:167], v[120:123]
	v_mfma_f32_16x16x32_bf16 v[116:119], v[156:159], v[164:167], v[116:119]
	v_mfma_f32_16x16x32_bf16 v[104:107], v[148:151], v[172:175], v[104:107]
	v_mfma_f32_16x16x32_bf16 v[100:103], v[156:159], v[172:175], v[100:103]
	v_mfma_f32_16x16x32_bf16 v[88:91], v[148:151], v[180:183], v[88:91]
	v_mfma_f32_16x16x32_bf16 v[84:87], v[156:159], v[180:183], v[84:87]
	v_mfma_f32_16x16x32_bf16 v[70:73], v[148:151], v[198:201], v[72:75]
	v_mfma_f32_16x16x32_bf16 v[66:69], v[156:159], v[198:201], v[66:69]
	v_mfma_f32_16x16x32_bf16 v[120:123], v[152:155], v[168:171], v[120:123]
	v_mfma_f32_16x16x32_bf16 v[116:119], v[160:163], v[168:171], v[116:119]
	v_mfma_f32_16x16x32_bf16 v[104:107], v[152:155], v[176:179], v[104:107]
	v_mfma_f32_16x16x32_bf16 v[100:103], v[160:163], v[176:179], v[100:103]
	v_mfma_f32_16x16x32_bf16 v[88:91], v[152:155], v[184:187], v[88:91]
	v_mfma_f32_16x16x32_bf16 v[84:87], v[160:163], v[184:187], v[84:87]
	v_mfma_f32_16x16x32_bf16 v[72:75], v[152:155], v[214:217], v[70:73]
	v_mfma_f32_16x16x32_bf16 v[68:71], v[160:163], v[214:217], v[66:69]
	s_setprio 0
	s_barrier
	v_mov_b32_e32 v64, v193
	ds_read_b128 v[164:167], v197 offset:49152
	ds_read_b128 v[168:171], v197 offset:50176
	ds_read_b128 v[172:175], v197 offset:51200
	ds_read_b128 v[176:179], v197 offset:52224
	ds_read_b128 v[180:183], v197 offset:53248
	ds_read_b128 v[184:187], v197 offset:54272
	ds_read_b128 v[198:201], v197 offset:55296
	ds_read_b128 v[214:217], v197 offset:56320
	s_add_i32 s60, s85, s49
	v_lshl_add_u64 v[66:67], s[54:55], 0, v[64:65]
	v_lshl_add_u64 v[66:67], v[66:67], 0, s[24:25]
	s_mov_b32 m0, s60
	v_mov_b32_e32 v64, v195
	global_load_lds_dwordx4 v[66:67], off
	s_add_i32 m0, s60, 0x2000
	s_nop 0
	v_lshl_add_u64 v[66:67], s[54:55], 0, v[64:65]
	s_add_u32 s54, s54, 0x20080
	v_lshl_add_u64 v[66:67], v[66:67], 0, s[24:25]
	s_addc_u32 s55, s55, 0
	v_mov_b32_e32 v64, v193
	s_add_i32 s60, s87, s49
	global_load_lds_dwordx4 v[66:67], off
	s_mov_b32 m0, s60
	s_nop 0
	global_load_lds_dwordx4 v64, s[54:55]
	v_mov_b32_e32 v64, v195
	s_add_i32 m0, s60, 0x2000
	s_nop 0
	global_load_lds_dwordx4 v64, s[54:55]
	v_mov_b32_e32 v64, v192
	s_mov_b32 m0, s22
	v_lshl_add_u64 v[66:67], s[2:3], 0, v[64:65]
	v_lshl_add_u64 v[66:67], v[66:67], 0, s[24:25]
	v_mov_b32_e32 v64, v194
	global_load_lds_dwordx4 v[66:67], off
	s_mov_b32 m0, s58
	v_lshl_add_u64 v[66:67], s[2:3], 0, v[64:65]
	v_lshl_add_u64 v[66:67], v[66:67], 0, s[24:25]
	global_load_lds_dwordx4 v[66:67], off
	s_waitcnt vmcnt(8)
	s_waitcnt lgkmcnt(0)
	s_barrier
	s_setprio 1
	s_waitcnt lgkmcnt(0)
	v_mfma_f32_16x16x32_bf16 v[60:63], v[132:135], v[164:167], v[60:63]
	v_mfma_f32_16x16x32_bf16 v[56:59], v[140:143], v[164:167], v[56:59]
	v_mfma_f32_16x16x32_bf16 v[44:47], v[132:135], v[172:175], v[44:47]
	v_mfma_f32_16x16x32_bf16 v[40:43], v[140:143], v[172:175], v[40:43]
	v_mfma_f32_16x16x32_bf16 v[28:31], v[132:135], v[180:183], v[28:31]
	v_mfma_f32_16x16x32_bf16 v[24:27], v[140:143], v[180:183], v[24:27]
	v_mfma_f32_16x16x32_bf16 v[12:15], v[132:135], v[198:201], v[12:15]
	v_mfma_f32_16x16x32_bf16 v[8:11], v[140:143], v[198:201], v[8:11]
	v_mfma_f32_16x16x32_bf16 v[60:63], v[136:139], v[168:171], v[60:63]
	v_mfma_f32_16x16x32_bf16 v[56:59], v[144:147], v[168:171], v[56:59]
	v_mfma_f32_16x16x32_bf16 v[44:47], v[136:139], v[176:179], v[44:47]
	v_mfma_f32_16x16x32_bf16 v[40:43], v[144:147], v[176:179], v[40:43]
	v_mfma_f32_16x16x32_bf16 v[28:31], v[136:139], v[184:187], v[28:31]
	v_mfma_f32_16x16x32_bf16 v[24:27], v[144:147], v[184:187], v[24:27]
	v_mfma_f32_16x16x32_bf16 v[12:15], v[136:139], v[214:217], v[12:15]
	v_mfma_f32_16x16x32_bf16 v[8:11], v[144:147], v[214:217], v[8:11]
	s_setprio 0
	s_setprio 1
	v_mfma_f32_16x16x32_bf16 v[52:55], v[148:151], v[164:167], v[52:55]
	v_mfma_f32_16x16x32_bf16 v[48:51], v[156:159], v[164:167], v[48:51]
	v_mfma_f32_16x16x32_bf16 v[36:39], v[148:151], v[172:175], v[36:39]
	v_mfma_f32_16x16x32_bf16 v[32:35], v[156:159], v[172:175], v[32:35]
	v_mfma_f32_16x16x32_bf16 v[20:23], v[148:151], v[180:183], v[20:23]
	v_mfma_f32_16x16x32_bf16 v[16:19], v[156:159], v[180:183], v[16:19]
	v_mfma_f32_16x16x32_bf16 v[4:7], v[148:151], v[198:201], v[4:7]
	v_mfma_f32_16x16x32_bf16 v[0:3], v[156:159], v[198:201], v[0:3]
	v_mfma_f32_16x16x32_bf16 v[52:55], v[152:155], v[168:171], v[52:55]
	v_mfma_f32_16x16x32_bf16 v[48:51], v[160:163], v[168:171], v[48:51]
	v_mfma_f32_16x16x32_bf16 v[36:39], v[152:155], v[176:179], v[36:39]
	v_mfma_f32_16x16x32_bf16 v[32:35], v[160:163], v[176:179], v[32:35]
	v_mfma_f32_16x16x32_bf16 v[20:23], v[152:155], v[184:187], v[20:23]
	v_mfma_f32_16x16x32_bf16 v[16:19], v[160:163], v[184:187], v[16:19]
	v_mfma_f32_16x16x32_bf16 v[4:7], v[152:155], v[214:217], v[4:7]
	v_mfma_f32_16x16x32_bf16 v[0:3], v[160:163], v[214:217], v[0:3]
	s_setprio 0
	s_barrier
	s_add_u32 s94, s94, 0x100
	s_addc_u32 s95, 0, s95
	s_cmp_gt_u32 s77, 13
	s_cbranch_scc1 .LBB0_148

.LBB0_324:
	s_add_i32 s60, 0, 0x10000
	s_add_i32 s67, 0, 0x14000
	v_add_u32_e32 v64, s60, v140
	ds_read_b128 v[130:133], v64
	ds_read_b128 v[142:145], v64 offset:1024
	ds_read_b128 v[146:149], v64 offset:2048
	ds_read_b128 v[150:153], v64 offset:3072
	v_add_u32_e32 v64, s67, v140
	ds_read_b128 v[154:157], v64
	ds_read_b128 v[158:161], v64 offset:1024
	ds_read_b128 v[162:165], v64 offset:2048
	ds_read_b128 v[166:169], v64 offset:3072
	s_add_u32 s2, s94, 0xfffc0080
	s_addc_u32 s3, s95, -1
	s_cmp_eq_u32 s66, 12
	s_cselect_b32 s3, s41, s3
	s_cselect_b32 s2, s43, s2
	s_cselect_b32 s55, s62, s65
	s_cselect_b32 s54, s63, s64
	v_mov_b32_e32 v64, v136
	ds_read_b128 v[170:173], v141
	ds_read_b128 v[174:177], v141 offset:1024
	ds_read_b128 v[178:181], v141 offset:2048
	ds_read_b128 v[182:185], v141 offset:3072
	ds_read_b128 v[190:193], v141 offset:4096
	ds_read_b128 v[194:197], v141 offset:5120
	ds_read_b128 v[214:217], v141 offset:6144
	ds_read_b128 v[218:221], v141 offset:7168
	s_add_i32 m0, s17, 0xc000
	s_nop 0
	global_load_lds_dwordx4 v64, s[94:95]
	v_mov_b32_e32 v64, v138
	s_add_i32 m0, s17, 0xe000
	s_nop 0
	global_load_lds_dwordx4 v64, s[94:95]
	s_waitcnt vmcnt(8)
	s_waitcnt lgkmcnt(0)
	s_barrier
	s_setprio 1
	s_waitcnt lgkmcnt(0)
	v_mfma_f32_16x16x32_bf16 v[126:129], v[130:133], v[170:173], v[126:129]
	v_mfma_f32_16x16x32_bf16 v[122:125], v[146:149], v[170:173], v[122:125]
	v_mfma_f32_16x16x32_bf16 v[110:113], v[130:133], v[178:181], v[110:113]
	v_mfma_f32_16x16x32_bf16 v[106:109], v[146:149], v[178:181], v[106:109]
	v_mfma_f32_16x16x32_bf16 v[94:97], v[130:133], v[190:193], v[94:97]
	v_mfma_f32_16x16x32_bf16 v[90:93], v[146:149], v[190:193], v[90:93]
	v_mfma_f32_16x16x32_bf16 v[78:81], v[130:133], v[214:217], v[78:81]
	v_mfma_f32_16x16x32_bf16 v[74:77], v[146:149], v[214:217], v[74:77]
	v_mfma_f32_16x16x32_bf16 v[126:129], v[142:145], v[174:177], v[126:129]
	v_mfma_f32_16x16x32_bf16 v[122:125], v[150:153], v[174:177], v[122:125]
	v_mfma_f32_16x16x32_bf16 v[110:113], v[142:145], v[182:185], v[110:113]
	v_mfma_f32_16x16x32_bf16 v[106:109], v[150:153], v[182:185], v[106:109]
	v_mfma_f32_16x16x32_bf16 v[94:97], v[142:145], v[194:197], v[94:97]
	v_mfma_f32_16x16x32_bf16 v[90:93], v[150:153], v[194:197], v[90:93]
	v_mfma_f32_16x16x32_bf16 v[78:81], v[142:145], v[218:221], v[78:81]
	v_mfma_f32_16x16x32_bf16 v[74:77], v[150:153], v[218:221], v[74:77]
	s_setprio 0
	s_setprio 1
	v_mfma_f32_16x16x32_bf16 v[118:121], v[154:157], v[170:173], v[118:121]
	v_mfma_f32_16x16x32_bf16 v[114:117], v[162:165], v[170:173], v[114:117]
	v_mfma_f32_16x16x32_bf16 v[102:105], v[154:157], v[178:181], v[102:105]
	v_mfma_f32_16x16x32_bf16 v[98:101], v[162:165], v[178:181], v[98:101]
	v_mfma_f32_16x16x32_bf16 v[86:89], v[154:157], v[190:193], v[86:89]
	v_mfma_f32_16x16x32_bf16 v[82:85], v[162:165], v[190:193], v[82:85]
	v_mfma_f32_16x16x32_bf16 v[70:73], v[154:157], v[214:217], v[70:73]
	v_mfma_f32_16x16x32_bf16 v[66:69], v[162:165], v[214:217], v[66:69]
	v_mfma_f32_16x16x32_bf16 v[118:121], v[158:161], v[174:177], v[118:121]
	v_mfma_f32_16x16x32_bf16 v[114:117], v[166:169], v[174:177], v[114:117]
	v_mfma_f32_16x16x32_bf16 v[102:105], v[158:161], v[182:185], v[102:105]
	v_mfma_f32_16x16x32_bf16 v[98:101], v[166:169], v[182:185], v[98:101]
	v_mfma_f32_16x16x32_bf16 v[86:89], v[158:161], v[194:197], v[86:89]
	v_mfma_f32_16x16x32_bf16 v[82:85], v[166:169], v[194:197], v[82:85]
	v_mfma_f32_16x16x32_bf16 v[70:73], v[158:161], v[218:221], v[70:73]
	v_mfma_f32_16x16x32_bf16 v[66:69], v[166:169], v[218:221], v[66:69]
	s_setprio 0
	s_barrier
	v_mov_b32_e32 v64, v137
	s_add_i32 s60, s60, s11
	ds_read_b128 v[170:173], v141 offset:16384
	ds_read_b128 v[174:177], v141 offset:17408
	ds_read_b128 v[178:181], v141 offset:18432
	ds_read_b128 v[182:185], v141 offset:19456
	ds_read_b128 v[190:193], v141 offset:20480
	ds_read_b128 v[194:197], v141 offset:21504
	ds_read_b128 v[214:217], v141 offset:22528
	ds_read_b128 v[218:221], v141 offset:23552
	s_mov_b32 m0, s60
	s_nop 0
	global_load_lds_dwordx4 v64, s[54:55]
	v_mov_b32_e32 v64, v139
	s_add_i32 m0, s60, 0x2000
	s_add_u32 s60, s54, 0x40000
	global_load_lds_dwordx4 v64, s[54:55]
	s_addc_u32 s61, s55, 0
	v_mov_b32_e32 v64, v137
	s_add_i32 s67, s67, s11
	s_mov_b32 m0, s67
	s_nop 0
	global_load_lds_dwordx4 v64, s[60:61]
	v_mov_b32_e32 v64, v139
	s_add_i32 m0, s67, 0x2000
	s_nop 0
	global_load_lds_dwordx4 v64, s[60:61]
	v_mov_b32_e32 v64, v136
	s_mov_b32 m0, s17
	s_nop 0
	global_load_lds_dwordx4 v64, s[2:3]
	v_mov_b32_e32 v64, v138
	s_mov_b32 m0, s22
	s_nop 0
	global_load_lds_dwordx4 v64, s[2:3]
	s_waitcnt vmcnt(8)
	s_waitcnt lgkmcnt(0)
	s_barrier
	s_setprio 1
	s_waitcnt lgkmcnt(0)
	v_mfma_f32_16x16x32_bf16 v[60:63], v[130:133], v[170:173], v[60:63]
	v_mfma_f32_16x16x32_bf16 v[56:59], v[146:149], v[170:173], v[56:59]
	v_mfma_f32_16x16x32_bf16 v[44:47], v[130:133], v[178:181], v[44:47]
	v_mfma_f32_16x16x32_bf16 v[40:43], v[146:149], v[178:181], v[40:43]
	v_mfma_f32_16x16x32_bf16 v[28:31], v[130:133], v[190:193], v[28:31]
	v_mfma_f32_16x16x32_bf16 v[24:27], v[146:149], v[190:193], v[24:27]
	v_mfma_f32_16x16x32_bf16 v[12:15], v[130:133], v[214:217], v[12:15]
	v_mfma_f32_16x16x32_bf16 v[8:11], v[146:149], v[214:217], v[8:11]
	v_mfma_f32_16x16x32_bf16 v[60:63], v[142:145], v[174:177], v[60:63]
	v_mfma_f32_16x16x32_bf16 v[56:59], v[150:153], v[174:177], v[56:59]
	v_mfma_f32_16x16x32_bf16 v[44:47], v[142:145], v[182:185], v[44:47]
	v_mfma_f32_16x16x32_bf16 v[40:43], v[150:153], v[182:185], v[40:43]
	v_mfma_f32_16x16x32_bf16 v[28:31], v[142:145], v[194:197], v[28:31]
	v_mfma_f32_16x16x32_bf16 v[24:27], v[150:153], v[194:197], v[24:27]
	v_mfma_f32_16x16x32_bf16 v[12:15], v[142:145], v[218:221], v[12:15]
	v_mfma_f32_16x16x32_bf16 v[8:11], v[150:153], v[218:221], v[8:11]
	s_setprio 0
	s_setprio 1
	v_mfma_f32_16x16x32_bf16 v[52:55], v[154:157], v[170:173], v[52:55]
	v_mfma_f32_16x16x32_bf16 v[48:51], v[162:165], v[170:173], v[48:51]
	v_mfma_f32_16x16x32_bf16 v[36:39], v[154:157], v[178:181], v[36:39]
	v_mfma_f32_16x16x32_bf16 v[32:35], v[162:165], v[178:181], v[32:35]
	v_mfma_f32_16x16x32_bf16 v[20:23], v[154:157], v[190:193], v[20:23]
	v_mfma_f32_16x16x32_bf16 v[16:19], v[162:165], v[190:193], v[16:19]
	v_mfma_f32_16x16x32_bf16 v[4:7], v[154:157], v[214:217], v[4:7]
	v_mfma_f32_16x16x32_bf16 v[0:3], v[162:165], v[214:217], v[0:3]
	v_mfma_f32_16x16x32_bf16 v[52:55], v[158:161], v[174:177], v[52:55]
	v_mfma_f32_16x16x32_bf16 v[48:51], v[166:169], v[174:177], v[48:51]
	v_mfma_f32_16x16x32_bf16 v[36:39], v[158:161], v[182:185], v[36:39]
	v_mfma_f32_16x16x32_bf16 v[32:35], v[166:169], v[182:185], v[32:35]
	v_mfma_f32_16x16x32_bf16 v[20:23], v[158:161], v[194:197], v[20:23]
	v_mfma_f32_16x16x32_bf16 v[16:19], v[166:169], v[194:197], v[16:19]
	v_mfma_f32_16x16x32_bf16 v[4:7], v[158:161], v[218:221], v[4:7]
	v_mfma_f32_16x16x32_bf16 v[0:3], v[166:169], v[218:221], v[0:3]
	s_setprio 0
	s_barrier
	s_add_i32 s67, 0, 0x18000
	v_add_u32_e32 v64, s67, v140
	s_add_i32 s68, 0, 0x1c000
	ds_read_b128 v[130:133], v64
	ds_read_b128 v[142:145], v64 offset:1024
	ds_read_b128 v[146:149], v64 offset:2048
	ds_read_b128 v[150:153], v64 offset:3072
	v_add_u32_e32 v64, s68, v140
	ds_read_b128 v[154:157], v64
	ds_read_b128 v[158:161], v64 offset:1024
	ds_read_b128 v[162:165], v64 offset:2048
	ds_read_b128 v[166:169], v64 offset:3072
	s_add_u32 s60, s2, 0x40000
	v_mov_b32_e32 v64, v136
	s_mov_b32 m0, s49
	ds_read_b128 v[170:173], v141 offset:32768
	ds_read_b128 v[174:177], v141 offset:33792
	ds_read_b128 v[178:181], v141 offset:34816
	ds_read_b128 v[182:185], v141 offset:35840
	ds_read_b128 v[190:193], v141 offset:36864
	ds_read_b128 v[194:197], v141 offset:37888
	ds_read_b128 v[214:217], v141 offset:38912
	ds_read_b128 v[218:221], v141 offset:39936
	s_addc_u32 s61, s3, 0
	s_nop 0
	global_load_lds_dwordx4 v64, s[60:61]
	v_mov_b32_e32 v64, v138
	s_mov_b32 m0, s50
	s_nop 0
	global_load_lds_dwordx4 v64, s[60:61]
	s_waitcnt vmcnt(8)
	s_waitcnt lgkmcnt(0)
	s_barrier
	s_setprio 1
	s_waitcnt lgkmcnt(0)
	v_mfma_f32_16x16x32_bf16 v[126:129], v[130:133], v[170:173], v[126:129]
	v_mfma_f32_16x16x32_bf16 v[122:125], v[146:149], v[170:173], v[122:125]
	v_mfma_f32_16x16x32_bf16 v[110:113], v[130:133], v[178:181], v[110:113]
	v_mfma_f32_16x16x32_bf16 v[106:109], v[146:149], v[178:181], v[106:109]
	v_mfma_f32_16x16x32_bf16 v[94:97], v[130:133], v[190:193], v[94:97]
	v_mfma_f32_16x16x32_bf16 v[90:93], v[146:149], v[190:193], v[90:93]
	v_mfma_f32_16x16x32_bf16 v[78:81], v[130:133], v[214:217], v[78:81]
	v_mfma_f32_16x16x32_bf16 v[74:77], v[146:149], v[214:217], v[74:77]
	v_mfma_f32_16x16x32_bf16 v[126:129], v[142:145], v[174:177], v[126:129]
	v_mfma_f32_16x16x32_bf16 v[122:125], v[150:153], v[174:177], v[122:125]
	v_mfma_f32_16x16x32_bf16 v[110:113], v[142:145], v[182:185], v[110:113]
	v_mfma_f32_16x16x32_bf16 v[106:109], v[150:153], v[182:185], v[106:109]
	v_mfma_f32_16x16x32_bf16 v[94:97], v[142:145], v[194:197], v[94:97]
	v_mfma_f32_16x16x32_bf16 v[90:93], v[150:153], v[194:197], v[90:93]
	v_mfma_f32_16x16x32_bf16 v[78:81], v[142:145], v[218:221], v[78:81]
	v_mfma_f32_16x16x32_bf16 v[74:77], v[150:153], v[218:221], v[74:77]
	s_setprio 0
	s_setprio 1
	v_mfma_f32_16x16x32_bf16 v[118:121], v[154:157], v[170:173], v[118:121]
	v_mfma_f32_16x16x32_bf16 v[114:117], v[162:165], v[170:173], v[114:117]
	v_mfma_f32_16x16x32_bf16 v[102:105], v[154:157], v[178:181], v[102:105]
	v_mfma_f32_16x16x32_bf16 v[98:101], v[162:165], v[178:181], v[98:101]
	v_mfma_f32_16x16x32_bf16 v[86:89], v[154:157], v[190:193], v[86:89]
	v_mfma_f32_16x16x32_bf16 v[82:85], v[162:165], v[190:193], v[82:85]
	v_mfma_f32_16x16x32_bf16 v[70:73], v[154:157], v[214:217], v[70:73]
	v_mfma_f32_16x16x32_bf16 v[66:69], v[162:165], v[214:217], v[66:69]
	v_mfma_f32_16x16x32_bf16 v[118:121], v[158:161], v[174:177], v[118:121]
	v_mfma_f32_16x16x32_bf16 v[114:117], v[166:169], v[174:177], v[114:117]
	v_mfma_f32_16x16x32_bf16 v[102:105], v[158:161], v[182:185], v[102:105]
	v_mfma_f32_16x16x32_bf16 v[98:101], v[166:169], v[182:185], v[98:101]
	v_mfma_f32_16x16x32_bf16 v[86:89], v[158:161], v[194:197], v[86:89]
	v_mfma_f32_16x16x32_bf16 v[82:85], v[166:169], v[194:197], v[82:85]
	v_mfma_f32_16x16x32_bf16 v[70:73], v[158:161], v[218:221], v[70:73]
	v_mfma_f32_16x16x32_bf16 v[66:69], v[166:169], v[218:221], v[66:69]
	s_setprio 0
	s_barrier
	v_mov_b32_e32 v64, v137
	ds_read_b128 v[170:173], v141 offset:49152
	ds_read_b128 v[174:177], v141 offset:50176
	ds_read_b128 v[178:181], v141 offset:51200
	ds_read_b128 v[182:185], v141 offset:52224
	ds_read_b128 v[190:193], v141 offset:53248
	ds_read_b128 v[194:197], v141 offset:54272
	ds_read_b128 v[214:217], v141 offset:55296
	ds_read_b128 v[218:221], v141 offset:56320
	s_add_i32 s60, s67, s11
	v_lshl_add_u64 v[134:135], s[54:55], 0, v[64:65]
	v_lshl_add_u64 v[134:135], v[134:135], 0, s[24:25]
	s_mov_b32 m0, s60
	v_mov_b32_e32 v64, v139
	global_load_lds_dwordx4 v[134:135], off
	s_add_i32 m0, s60, 0x2000
	s_nop 0
	v_lshl_add_u64 v[134:135], s[54:55], 0, v[64:65]
	s_add_u32 s54, s54, 0x40080
	v_lshl_add_u64 v[134:135], v[134:135], 0, s[24:25]
	s_addc_u32 s55, s55, 0
	v_mov_b32_e32 v64, v137
	s_add_i32 s60, s68, s11
	global_load_lds_dwordx4 v[134:135], off
	s_mov_b32 m0, s60
	s_nop 0
	global_load_lds_dwordx4 v64, s[54:55]
	v_mov_b32_e32 v64, v139
	s_add_i32 m0, s60, 0x2000
	s_nop 0
	global_load_lds_dwordx4 v64, s[54:55]
	v_mov_b32_e32 v64, v136
	s_mov_b32 m0, s51
	v_lshl_add_u64 v[134:135], s[2:3], 0, v[64:65]
	v_lshl_add_u64 v[134:135], v[134:135], 0, s[24:25]
	v_mov_b32_e32 v64, v138
	global_load_lds_dwordx4 v[134:135], off
	s_mov_b32 m0, s52
	v_lshl_add_u64 v[134:135], s[2:3], 0, v[64:65]
	v_lshl_add_u64 v[134:135], v[134:135], 0, s[24:25]
	global_load_lds_dwordx4 v[134:135], off
	s_waitcnt vmcnt(8)
	s_waitcnt lgkmcnt(0)
	s_barrier
	s_setprio 1
	s_waitcnt lgkmcnt(0)
	v_mfma_f32_16x16x32_bf16 v[60:63], v[130:133], v[170:173], v[60:63]
	v_mfma_f32_16x16x32_bf16 v[56:59], v[146:149], v[170:173], v[56:59]
	v_mfma_f32_16x16x32_bf16 v[44:47], v[130:133], v[178:181], v[44:47]
	v_mfma_f32_16x16x32_bf16 v[40:43], v[146:149], v[178:181], v[40:43]
	v_mfma_f32_16x16x32_bf16 v[28:31], v[130:133], v[190:193], v[28:31]
	v_mfma_f32_16x16x32_bf16 v[24:27], v[146:149], v[190:193], v[24:27]
	v_mfma_f32_16x16x32_bf16 v[12:15], v[130:133], v[214:217], v[12:15]
	v_mfma_f32_16x16x32_bf16 v[8:11], v[146:149], v[214:217], v[8:11]
	v_mfma_f32_16x16x32_bf16 v[60:63], v[142:145], v[174:177], v[60:63]
	v_mfma_f32_16x16x32_bf16 v[56:59], v[150:153], v[174:177], v[56:59]
	v_mfma_f32_16x16x32_bf16 v[44:47], v[142:145], v[182:185], v[44:47]
	v_mfma_f32_16x16x32_bf16 v[40:43], v[150:153], v[182:185], v[40:43]
	v_mfma_f32_16x16x32_bf16 v[28:31], v[142:145], v[194:197], v[28:31]
	v_mfma_f32_16x16x32_bf16 v[24:27], v[150:153], v[194:197], v[24:27]
	v_mfma_f32_16x16x32_bf16 v[12:15], v[142:145], v[218:221], v[12:15]
	v_mfma_f32_16x16x32_bf16 v[8:11], v[150:153], v[218:221], v[8:11]
	s_setprio 0
	s_setprio 1
	v_mfma_f32_16x16x32_bf16 v[52:55], v[154:157], v[170:173], v[52:55]
	v_mfma_f32_16x16x32_bf16 v[48:51], v[162:165], v[170:173], v[48:51]
	v_mfma_f32_16x16x32_bf16 v[36:39], v[154:157], v[178:181], v[36:39]
	v_mfma_f32_16x16x32_bf16 v[32:35], v[162:165], v[178:181], v[32:35]
	v_mfma_f32_16x16x32_bf16 v[20:23], v[154:157], v[190:193], v[20:23]
	v_mfma_f32_16x16x32_bf16 v[16:19], v[162:165], v[190:193], v[16:19]
	v_mfma_f32_16x16x32_bf16 v[4:7], v[154:157], v[214:217], v[4:7]
	v_mfma_f32_16x16x32_bf16 v[0:3], v[162:165], v[214:217], v[0:3]
	v_mfma_f32_16x16x32_bf16 v[52:55], v[158:161], v[174:177], v[52:55]
	v_mfma_f32_16x16x32_bf16 v[48:51], v[166:169], v[174:177], v[48:51]
	v_mfma_f32_16x16x32_bf16 v[36:39], v[158:161], v[182:185], v[36:39]
	v_mfma_f32_16x16x32_bf16 v[32:35], v[166:169], v[182:185], v[32:35]
	v_mfma_f32_16x16x32_bf16 v[20:23], v[158:161], v[194:197], v[20:23]
	v_mfma_f32_16x16x32_bf16 v[16:19], v[166:169], v[194:197], v[16:19]
	v_mfma_f32_16x16x32_bf16 v[4:7], v[158:161], v[218:221], v[4:7]
	v_mfma_f32_16x16x32_bf16 v[0:3], v[166:169], v[218:221], v[0:3]
	s_setprio 0
	s_barrier
	s_add_i32 s66, s66, 2
	s_add_u32 s94, s94, 0x100
	s_addc_u32 s95, s95, 0
	s_add_u32 s64, s64, 0x100
	s_addc_u32 s65, s65, 0
	s_cmp_gt_u32 s66, 13
	s_cbranch_scc0 .LBB0_324
	s_and_b64 vcc, exec, s[82:83]
	s_movk_i32 s62, 0x89f
	s_movk_i32 s63, 0xca0
	s_cbranch_vccz .LBB0_327
	s_barrier

.LBB0_695:
	s_add_i32 s60, 0, 0x10000
	s_add_i32 s61, 0, 0x14000
	v_add_u32_e32 v64, s60, v134
	ds_read_b128 v[136:139], v64
	ds_read_b128 v[140:143], v64 offset:1024
	ds_read_b128 v[144:147], v64 offset:2048
	ds_read_b128 v[148:151], v64 offset:3072
	v_add_u32_e32 v64, s61, v134
	ds_read_b128 v[152:155], v64
	ds_read_b128 v[156:159], v64 offset:1024
	ds_read_b128 v[160:163], v64 offset:2048
	ds_read_b128 v[164:167], v64 offset:3072
	s_add_u32 s2, s88, 0xfda00080
	s_addc_u32 s3, s89, -1
	s_cmp_lg_u32 s57, 60
	s_cselect_b32 s54, s2, 0
	s_cselect_b32 s55, s3, 0
	s_add_u32 s2, s86, s54
	s_addc_u32 s3, s87, s55
	s_add_u32 s54, s46, s54
	s_addc_u32 s55, s47, s55
	s_add_i32 m0, s17, 0xc000
	v_mov_b32_e32 v64, v130
	s_add_u32 s58, s53, s88
	ds_read_b128 v[168:171], v135
	ds_read_b128 v[172:175], v135 offset:1024
	ds_read_b128 v[176:179], v135 offset:2048
	ds_read_b128 v[180:183], v135 offset:3072
	ds_read_b128 v[184:187], v135 offset:4096
	ds_read_b128 v[190:193], v135 offset:5120
	ds_read_b128 v[194:197], v135 offset:6144
	ds_read_b128 v[198:201], v135 offset:7168
	s_addc_u32 s59, s56, s89
	global_load_lds_dwordx4 v64, s[58:59]
	v_mov_b32_e32 v64, v132
	s_add_i32 m0, s17, 0xe000
	s_nop 0
	global_load_lds_dwordx4 v64, s[58:59]
	s_waitcnt vmcnt(8)
	s_waitcnt lgkmcnt(0)
	s_barrier
	s_setprio 1
	s_waitcnt lgkmcnt(0)
	v_mfma_f32_16x16x32_bf16 v[48:51], v[136:139], v[168:171], v[48:51]
	v_mfma_f32_16x16x32_bf16 v[44:47], v[144:147], v[168:171], v[44:47]
	v_mfma_f32_16x16x32_bf16 v[4:7], v[136:139], v[176:179], v[4:7]
	v_mfma_f32_16x16x32_bf16 v[0:3], v[144:147], v[176:179], v[0:3]
	v_mfma_f32_16x16x32_bf16 v[36:39], v[136:139], v[184:187], v[36:39]
	v_mfma_f32_16x16x32_bf16 v[32:35], v[144:147], v[184:187], v[32:35]
	v_mfma_f32_16x16x32_bf16 v[78:81], v[136:139], v[194:197], v[78:81]
	v_mfma_f32_16x16x32_bf16 v[74:77], v[144:147], v[194:197], v[74:77]
	v_mfma_f32_16x16x32_bf16 v[48:51], v[140:143], v[172:175], v[48:51]
	v_mfma_f32_16x16x32_bf16 v[44:47], v[148:151], v[172:175], v[44:47]
	v_mfma_f32_16x16x32_bf16 v[4:7], v[140:143], v[180:183], v[4:7]
	v_mfma_f32_16x16x32_bf16 v[0:3], v[148:151], v[180:183], v[0:3]
	v_mfma_f32_16x16x32_bf16 v[36:39], v[140:143], v[190:193], v[36:39]
	v_mfma_f32_16x16x32_bf16 v[32:35], v[148:151], v[190:193], v[32:35]
	v_mfma_f32_16x16x32_bf16 v[78:81], v[140:143], v[198:201], v[78:81]
	v_mfma_f32_16x16x32_bf16 v[74:77], v[148:151], v[198:201], v[74:77]
	s_setprio 0
	s_setprio 1
	v_mfma_f32_16x16x32_bf16 v[16:19], v[152:155], v[168:171], v[16:19]
	v_mfma_f32_16x16x32_bf16 v[8:11], v[160:163], v[168:171], v[8:11]
	v_mfma_f32_16x16x32_bf16 v[24:27], v[152:155], v[176:179], v[24:27]
	v_mfma_f32_16x16x32_bf16 v[28:31], v[160:163], v[176:179], v[28:31]
	v_mfma_f32_16x16x32_bf16 v[56:59], v[152:155], v[184:187], v[56:59]
	v_mfma_f32_16x16x32_bf16 v[66:69], v[160:163], v[184:187], v[66:69]
	v_mfma_f32_16x16x32_bf16 v[86:89], v[152:155], v[194:197], v[86:89]
	v_mfma_f32_16x16x32_bf16 v[94:97], v[160:163], v[194:197], v[94:97]
	v_mfma_f32_16x16x32_bf16 v[16:19], v[156:159], v[172:175], v[16:19]
	v_mfma_f32_16x16x32_bf16 v[8:11], v[164:167], v[172:175], v[8:11]
	v_mfma_f32_16x16x32_bf16 v[24:27], v[156:159], v[180:183], v[24:27]
	v_mfma_f32_16x16x32_bf16 v[28:31], v[164:167], v[180:183], v[28:31]
	v_mfma_f32_16x16x32_bf16 v[56:59], v[156:159], v[190:193], v[56:59]
	v_mfma_f32_16x16x32_bf16 v[66:69], v[164:167], v[190:193], v[66:69]
	v_mfma_f32_16x16x32_bf16 v[86:89], v[156:159], v[198:201], v[86:89]
	v_mfma_f32_16x16x32_bf16 v[94:97], v[164:167], v[198:201], v[94:97]
	s_setprio 0
	s_barrier
	v_mov_b32_e32 v64, v131
	s_add_i32 s58, s60, s11
	ds_read_b128 v[168:171], v135 offset:16384
	ds_read_b128 v[172:175], v135 offset:17408
	ds_read_b128 v[176:179], v135 offset:18432
	ds_read_b128 v[180:183], v135 offset:19456
	ds_read_b128 v[184:187], v135 offset:20480
	ds_read_b128 v[190:193], v135 offset:21504
	ds_read_b128 v[194:197], v135 offset:22528
	ds_read_b128 v[198:201], v135 offset:23552
	s_mov_b32 m0, s58
	s_nop 0
	global_load_lds_dwordx4 v64, s[54:55]
	v_mov_b32_e32 v64, v133
	s_add_i32 m0, s58, 0x2000
	s_add_u32 s58, s54, 0x100000
	global_load_lds_dwordx4 v64, s[54:55]
	s_addc_u32 s59, s55, 0
	v_mov_b32_e32 v64, v131
	s_add_i32 s60, s61, s11
	s_mov_b32 m0, s60
	s_nop 0
	global_load_lds_dwordx4 v64, s[58:59]
	v_mov_b32_e32 v64, v133
	s_add_i32 m0, s60, 0x2000
	s_nop 0
	global_load_lds_dwordx4 v64, s[58:59]
	v_mov_b32_e32 v64, v130
	s_mov_b32 m0, s17
	s_nop 0
	global_load_lds_dwordx4 v64, s[2:3]
	v_mov_b32_e32 v64, v132
	s_mov_b32 m0, s41
	s_nop 0
	global_load_lds_dwordx4 v64, s[2:3]
	s_waitcnt vmcnt(8)
	s_waitcnt lgkmcnt(0)
	s_barrier
	s_setprio 1
	s_waitcnt lgkmcnt(0)
	v_mfma_f32_16x16x32_bf16 v[106:109], v[136:139], v[168:171], v[106:109]
	v_mfma_f32_16x16x32_bf16 v[102:105], v[144:147], v[168:171], v[102:105]
	v_mfma_f32_16x16x32_bf16 v[126:129], v[136:139], v[176:179], v[126:129]
	v_mfma_f32_16x16x32_bf16 v[122:125], v[144:147], v[176:179], v[122:125]
	v_mfma_f32_16x16x32_bf16 v[90:93], v[136:139], v[184:187], v[90:93]
	v_mfma_f32_16x16x32_bf16 v[82:85], v[144:147], v[184:187], v[82:85]
	v_mfma_f32_16x16x32_bf16 v[52:55], v[136:139], v[194:197], v[52:55]
	v_mfma_f32_16x16x32_bf16 v[40:43], v[144:147], v[194:197], v[40:43]
	v_mfma_f32_16x16x32_bf16 v[106:109], v[140:143], v[172:175], v[106:109]
	v_mfma_f32_16x16x32_bf16 v[102:105], v[148:151], v[172:175], v[102:105]
	v_mfma_f32_16x16x32_bf16 v[126:129], v[140:143], v[180:183], v[126:129]
	v_mfma_f32_16x16x32_bf16 v[122:125], v[148:151], v[180:183], v[122:125]
	v_mfma_f32_16x16x32_bf16 v[90:93], v[140:143], v[190:193], v[90:93]
	v_mfma_f32_16x16x32_bf16 v[82:85], v[148:151], v[190:193], v[82:85]
	v_mfma_f32_16x16x32_bf16 v[52:55], v[140:143], v[198:201], v[52:55]
	v_mfma_f32_16x16x32_bf16 v[40:43], v[148:151], v[198:201], v[40:43]
	s_setprio 0
	s_setprio 1
	v_mfma_f32_16x16x32_bf16 v[114:117], v[152:155], v[168:171], v[114:117]
	v_mfma_f32_16x16x32_bf16 v[118:121], v[160:163], v[168:171], v[118:121]
	v_mfma_f32_16x16x32_bf16 v[110:113], v[152:155], v[176:179], v[110:113]
	v_mfma_f32_16x16x32_bf16 v[98:101], v[160:163], v[176:179], v[98:101]
	v_mfma_f32_16x16x32_bf16 v[70:73], v[152:155], v[184:187], v[70:73]
	v_mfma_f32_16x16x32_bf16 v[60:63], v[160:163], v[184:187], v[60:63]
	v_mfma_f32_16x16x32_bf16 v[20:23], v[152:155], v[194:197], v[20:23]
	v_mfma_f32_16x16x32_bf16 v[12:15], v[160:163], v[194:197], v[12:15]
	v_mfma_f32_16x16x32_bf16 v[114:117], v[156:159], v[172:175], v[114:117]
	v_mfma_f32_16x16x32_bf16 v[118:121], v[164:167], v[172:175], v[118:121]
	v_mfma_f32_16x16x32_bf16 v[110:113], v[156:159], v[180:183], v[110:113]
	v_mfma_f32_16x16x32_bf16 v[98:101], v[164:167], v[180:183], v[98:101]
	v_mfma_f32_16x16x32_bf16 v[70:73], v[156:159], v[190:193], v[70:73]
	v_mfma_f32_16x16x32_bf16 v[60:63], v[164:167], v[190:193], v[60:63]
	v_mfma_f32_16x16x32_bf16 v[20:23], v[156:159], v[198:201], v[20:23]
	v_mfma_f32_16x16x32_bf16 v[12:15], v[164:167], v[198:201], v[12:15]
	s_setprio 0
	s_barrier
	s_add_i32 s60, 0, 0x18000
	v_add_u32_e32 v64, s60, v134
	s_add_i32 s61, 0, 0x1c000
	ds_read_b128 v[136:139], v64
	ds_read_b128 v[140:143], v64 offset:1024
	ds_read_b128 v[144:147], v64 offset:2048
	ds_read_b128 v[148:151], v64 offset:3072
	v_add_u32_e32 v64, s61, v134
	ds_read_b128 v[152:155], v64
	ds_read_b128 v[156:159], v64 offset:1024
	ds_read_b128 v[160:163], v64 offset:2048
	ds_read_b128 v[164:167], v64 offset:3072
	s_add_u32 s58, s2, 0x100000
	v_mov_b32_e32 v64, v130
	s_mov_b32 m0, s49
	ds_read_b128 v[168:171], v135 offset:32768
	ds_read_b128 v[172:175], v135 offset:33792
	ds_read_b128 v[176:179], v135 offset:34816
	ds_read_b128 v[180:183], v135 offset:35840
	ds_read_b128 v[184:187], v135 offset:36864
	ds_read_b128 v[190:193], v135 offset:37888
	ds_read_b128 v[194:197], v135 offset:38912
	ds_read_b128 v[198:201], v135 offset:39936
	s_addc_u32 s59, s3, 0
	s_nop 0
	global_load_lds_dwordx4 v64, s[58:59]
	v_mov_b32_e32 v64, v132
	s_mov_b32 m0, s50
	s_nop 0
	global_load_lds_dwordx4 v64, s[58:59]
	s_waitcnt vmcnt(8)
	s_waitcnt lgkmcnt(0)
	s_barrier
	s_setprio 1
	s_waitcnt lgkmcnt(0)
	v_mfma_f32_16x16x32_bf16 v[48:51], v[136:139], v[168:171], v[48:51]
	v_mfma_f32_16x16x32_bf16 v[44:47], v[144:147], v[168:171], v[44:47]
	v_mfma_f32_16x16x32_bf16 v[4:7], v[136:139], v[176:179], v[4:7]
	v_mfma_f32_16x16x32_bf16 v[0:3], v[144:147], v[176:179], v[0:3]
	v_mfma_f32_16x16x32_bf16 v[36:39], v[136:139], v[184:187], v[36:39]
	v_mfma_f32_16x16x32_bf16 v[32:35], v[144:147], v[184:187], v[32:35]
	v_mfma_f32_16x16x32_bf16 v[78:81], v[136:139], v[194:197], v[78:81]
	v_mfma_f32_16x16x32_bf16 v[74:77], v[144:147], v[194:197], v[74:77]
	v_mfma_f32_16x16x32_bf16 v[48:51], v[140:143], v[172:175], v[48:51]
	v_mfma_f32_16x16x32_bf16 v[44:47], v[148:151], v[172:175], v[44:47]
	v_mfma_f32_16x16x32_bf16 v[4:7], v[140:143], v[180:183], v[4:7]
	v_mfma_f32_16x16x32_bf16 v[0:3], v[148:151], v[180:183], v[0:3]
	v_mfma_f32_16x16x32_bf16 v[36:39], v[140:143], v[190:193], v[36:39]
	v_mfma_f32_16x16x32_bf16 v[32:35], v[148:151], v[190:193], v[32:35]
	v_mfma_f32_16x16x32_bf16 v[78:81], v[140:143], v[198:201], v[78:81]
	v_mfma_f32_16x16x32_bf16 v[74:77], v[148:151], v[198:201], v[74:77]
	s_setprio 0
	s_setprio 1
	v_mfma_f32_16x16x32_bf16 v[16:19], v[152:155], v[168:171], v[16:19]
	v_mfma_f32_16x16x32_bf16 v[8:11], v[160:163], v[168:171], v[8:11]
	v_mfma_f32_16x16x32_bf16 v[24:27], v[152:155], v[176:179], v[24:27]
	v_mfma_f32_16x16x32_bf16 v[28:31], v[160:163], v[176:179], v[28:31]
	v_mfma_f32_16x16x32_bf16 v[56:59], v[152:155], v[184:187], v[56:59]
	v_mfma_f32_16x16x32_bf16 v[66:69], v[160:163], v[184:187], v[66:69]
	v_mfma_f32_16x16x32_bf16 v[86:89], v[152:155], v[194:197], v[86:89]
	v_mfma_f32_16x16x32_bf16 v[94:97], v[160:163], v[194:197], v[94:97]
	v_mfma_f32_16x16x32_bf16 v[16:19], v[156:159], v[172:175], v[16:19]
	v_mfma_f32_16x16x32_bf16 v[8:11], v[164:167], v[172:175], v[8:11]
	v_mfma_f32_16x16x32_bf16 v[24:27], v[156:159], v[180:183], v[24:27]
	v_mfma_f32_16x16x32_bf16 v[28:31], v[164:167], v[180:183], v[28:31]
	v_mfma_f32_16x16x32_bf16 v[56:59], v[156:159], v[190:193], v[56:59]
	v_mfma_f32_16x16x32_bf16 v[66:69], v[164:167], v[190:193], v[66:69]
	v_mfma_f32_16x16x32_bf16 v[86:89], v[156:159], v[198:201], v[86:89]
	v_mfma_f32_16x16x32_bf16 v[94:97], v[164:167], v[198:201], v[94:97]
	s_setprio 0
	s_barrier
	v_mov_b32_e32 v64, v131
	ds_read_b128 v[168:171], v135 offset:49152
	ds_read_b128 v[172:175], v135 offset:50176
	ds_read_b128 v[176:179], v135 offset:51200
	ds_read_b128 v[180:183], v135 offset:52224
	ds_read_b128 v[184:187], v135 offset:53248
	ds_read_b128 v[190:193], v135 offset:54272
	ds_read_b128 v[194:197], v135 offset:55296
	ds_read_b128 v[198:201], v135 offset:56320
	s_add_i32 s58, s60, s11
	v_lshl_add_u64 v[214:215], s[54:55], 0, v[64:65]
	v_lshl_add_u64 v[214:215], v[214:215], 0, s[24:25]
	s_mov_b32 m0, s58
	v_mov_b32_e32 v64, v133
	global_load_lds_dwordx4 v[214:215], off
	s_add_i32 m0, s58, 0x2000
	s_nop 0
	v_lshl_add_u64 v[214:215], s[54:55], 0, v[64:65]
	s_add_u32 s54, s54, 0x100080
	v_lshl_add_u64 v[214:215], v[214:215], 0, s[24:25]
	s_addc_u32 s55, s55, 0
	v_mov_b32_e32 v64, v131
	s_add_i32 s58, s61, s11
	global_load_lds_dwordx4 v[214:215], off
	s_mov_b32 m0, s58
	s_nop 0
	global_load_lds_dwordx4 v64, s[54:55]
	v_mov_b32_e32 v64, v133
	s_add_i32 m0, s58, 0x2000
	s_nop 0
	global_load_lds_dwordx4 v64, s[54:55]
	v_mov_b32_e32 v64, v130
	s_mov_b32 m0, s51
	v_lshl_add_u64 v[214:215], s[2:3], 0, v[64:65]
	v_lshl_add_u64 v[214:215], v[214:215], 0, s[24:25]
	v_mov_b32_e32 v64, v132
	global_load_lds_dwordx4 v[214:215], off
	s_mov_b32 m0, s52
	v_lshl_add_u64 v[214:215], s[2:3], 0, v[64:65]
	v_lshl_add_u64 v[214:215], v[214:215], 0, s[24:25]
	global_load_lds_dwordx4 v[214:215], off
	s_waitcnt vmcnt(8)
	s_waitcnt lgkmcnt(0)
	s_barrier
	s_setprio 1
	s_waitcnt lgkmcnt(0)
	v_mfma_f32_16x16x32_bf16 v[106:109], v[136:139], v[168:171], v[106:109]
	v_mfma_f32_16x16x32_bf16 v[102:105], v[144:147], v[168:171], v[102:105]
	v_mfma_f32_16x16x32_bf16 v[126:129], v[136:139], v[176:179], v[126:129]
	v_mfma_f32_16x16x32_bf16 v[122:125], v[144:147], v[176:179], v[122:125]
	v_mfma_f32_16x16x32_bf16 v[90:93], v[136:139], v[184:187], v[90:93]
	v_mfma_f32_16x16x32_bf16 v[82:85], v[144:147], v[184:187], v[82:85]
	v_mfma_f32_16x16x32_bf16 v[52:55], v[136:139], v[194:197], v[52:55]
	v_mfma_f32_16x16x32_bf16 v[40:43], v[144:147], v[194:197], v[40:43]
	v_mfma_f32_16x16x32_bf16 v[106:109], v[140:143], v[172:175], v[106:109]
	v_mfma_f32_16x16x32_bf16 v[102:105], v[148:151], v[172:175], v[102:105]
	v_mfma_f32_16x16x32_bf16 v[126:129], v[140:143], v[180:183], v[126:129]
	v_mfma_f32_16x16x32_bf16 v[122:125], v[148:151], v[180:183], v[122:125]
	v_mfma_f32_16x16x32_bf16 v[90:93], v[140:143], v[190:193], v[90:93]
	v_mfma_f32_16x16x32_bf16 v[82:85], v[148:151], v[190:193], v[82:85]
	v_mfma_f32_16x16x32_bf16 v[52:55], v[140:143], v[198:201], v[52:55]
	v_mfma_f32_16x16x32_bf16 v[40:43], v[148:151], v[198:201], v[40:43]
	s_setprio 0
	s_setprio 1
	v_mfma_f32_16x16x32_bf16 v[114:117], v[152:155], v[168:171], v[114:117]
	v_mfma_f32_16x16x32_bf16 v[118:121], v[160:163], v[168:171], v[118:121]
	v_mfma_f32_16x16x32_bf16 v[110:113], v[152:155], v[176:179], v[110:113]
	v_mfma_f32_16x16x32_bf16 v[98:101], v[160:163], v[176:179], v[98:101]
	v_mfma_f32_16x16x32_bf16 v[70:73], v[152:155], v[184:187], v[70:73]
	v_mfma_f32_16x16x32_bf16 v[60:63], v[160:163], v[184:187], v[60:63]
	v_mfma_f32_16x16x32_bf16 v[20:23], v[152:155], v[194:197], v[20:23]
	v_mfma_f32_16x16x32_bf16 v[12:15], v[160:163], v[194:197], v[12:15]
	v_mfma_f32_16x16x32_bf16 v[114:117], v[156:159], v[172:175], v[114:117]
	v_mfma_f32_16x16x32_bf16 v[118:121], v[164:167], v[172:175], v[118:121]
	v_mfma_f32_16x16x32_bf16 v[110:113], v[156:159], v[180:183], v[110:113]
	v_mfma_f32_16x16x32_bf16 v[98:101], v[164:167], v[180:183], v[98:101]
	v_mfma_f32_16x16x32_bf16 v[70:73], v[156:159], v[190:193], v[70:73]
	v_mfma_f32_16x16x32_bf16 v[60:63], v[164:167], v[190:193], v[60:63]
	v_mfma_f32_16x16x32_bf16 v[20:23], v[156:159], v[198:201], v[20:23]
	v_mfma_f32_16x16x32_bf16 v[12:15], v[164:167], v[198:201], v[12:15]
	s_setprio 0
	s_barrier
	s_add_i32 s57, s57, 2
	s_add_u32 s88, s88, 0x100
	s_addc_u32 s89, s89, 0
	s_cmp_gt_u32 s57, 61
	s_cbranch_scc0 .LBB0_695
	s_cmp_lt_u32 s48, 4
	s_cbranch_scc0 .LBB0_698
	s_barrier
